# stack on keep_v10: merged end-of-load-segment waits + s_setprio 0 before the last MFMA of each compute segment
# baseline (speedup 1.0000x reference)
.LBB0_182:
	s_add_u32 s6, s4, 0xfffc0080
	s_addc_u32 s7, s5, -1
	s_add_i32 s9, 0, 0x10000
	s_cmp_eq_u32 s53, 12
	s_cselect_b32 s27, s39, s7
	s_cselect_b32 s26, s49, s6
	v_add_u32_e32 v0, s9, v189
	s_cselect_b32 s7, s15, s52
	s_cselect_b32 s6, s50, s51
	s_add_i32 s83, 0, 0x14000
	ds_read_b128 v[130:133], v0
	ds_read_b128 v[134:137], v0 offset:1024
	ds_read_b128 v[162:165], v0 offset:2048
	ds_read_b128 v[166:169], v0 offset:3072
	v_add_u32_e32 v0, s83, v189
	ds_read_b128 v[170:173], v0
	ds_read_b128 v[174:177], v0 offset:1024
	ds_read_b128 v[178:181], v0 offset:2048
	ds_read_b128 v[182:185], v0 offset:3072
	v_lshl_add_u64 v[148:149], s[4:5], 0, v[158:159]
	s_add_i32 m0, s40, 0xc000
	ds_read_b128 v[196:199], v193
	ds_read_b128 v[200:203], v193 offset:1024
	ds_read_b128 v[204:207], v193 offset:2048
	ds_read_b128 v[208:211], v193 offset:3072
	ds_read_b128 v[212:215], v193 offset:4096
	ds_read_b128 v[216:219], v193 offset:5120
	ds_read_b128 v[220:223], v193 offset:6144
	ds_read_b128 v[224:227], v193 offset:7168
	global_load_lds_dwordx4 v[148:149], off
	s_add_i32 m0, s40, 0xe000
	v_lshl_add_u64 v[148:149], s[4:5], 0, v[160:161]
	global_load_lds_dwordx4 v[148:149], off
	s_waitcnt vmcnt(8) lgkmcnt(0)
	s_setprio 1
	s_barrier
	v_mfma_f32_16x16x32_bf16 v[126:129], v[130:133], v[196:199], v[126:129]
	v_mfma_f32_16x16x32_bf16 v[122:125], v[162:165], v[196:199], v[122:125]
	v_mfma_f32_16x16x32_bf16 v[118:121], v[130:133], v[204:207], v[118:121]
	v_mfma_f32_16x16x32_bf16 v[114:117], v[162:165], v[204:207], v[114:117]
	v_mfma_f32_16x16x32_bf16 v[102:105], v[130:133], v[212:215], v[102:105]
	v_mfma_f32_16x16x32_bf16 v[98:101], v[162:165], v[212:215], v[98:101]
	v_mfma_f32_16x16x32_bf16 v[86:89], v[130:133], v[220:223], v[86:89]
	v_mfma_f32_16x16x32_bf16 v[82:85], v[162:165], v[220:223], v[82:85]
	v_mfma_f32_16x16x32_bf16 v[126:129], v[134:137], v[200:203], v[126:129]
	v_mfma_f32_16x16x32_bf16 v[122:125], v[166:169], v[200:203], v[122:125]
	v_mfma_f32_16x16x32_bf16 v[118:121], v[134:137], v[208:211], v[118:121]
	v_mfma_f32_16x16x32_bf16 v[114:117], v[166:169], v[208:211], v[114:117]
	v_mfma_f32_16x16x32_bf16 v[102:105], v[134:137], v[216:219], v[102:105]
	v_mfma_f32_16x16x32_bf16 v[98:101], v[166:169], v[216:219], v[98:101]
	v_mfma_f32_16x16x32_bf16 v[86:89], v[134:137], v[224:227], v[86:89]
	v_mfma_f32_16x16x32_bf16 v[82:85], v[166:169], v[224:227], v[82:85]
	v_mfma_f32_16x16x32_bf16 v[110:113], v[170:173], v[196:199], v[110:113]
	v_mfma_f32_16x16x32_bf16 v[106:109], v[178:181], v[196:199], v[106:109]
	v_mfma_f32_16x16x32_bf16 v[94:97], v[170:173], v[204:207], v[94:97]
	v_mfma_f32_16x16x32_bf16 v[90:93], v[178:181], v[204:207], v[90:93]
	v_mfma_f32_16x16x32_bf16 v[78:81], v[170:173], v[212:215], v[78:81]
	v_mfma_f32_16x16x32_bf16 v[74:77], v[178:181], v[212:215], v[74:77]
	v_mfma_f32_16x16x32_bf16 v[70:73], v[170:173], v[220:223], v[70:73]
	v_mfma_f32_16x16x32_bf16 v[66:69], v[178:181], v[220:223], v[66:69]
	v_mfma_f32_16x16x32_bf16 v[110:113], v[174:177], v[200:203], v[110:113]
	v_mfma_f32_16x16x32_bf16 v[106:109], v[182:185], v[200:203], v[106:109]
	v_mfma_f32_16x16x32_bf16 v[94:97], v[174:177], v[208:211], v[94:97]
	v_mfma_f32_16x16x32_bf16 v[90:93], v[182:185], v[208:211], v[90:93]
	v_mfma_f32_16x16x32_bf16 v[78:81], v[174:177], v[216:219], v[78:81]
	v_mfma_f32_16x16x32_bf16 v[74:77], v[182:185], v[216:219], v[74:77]
	v_mfma_f32_16x16x32_bf16 v[70:73], v[174:177], v[224:227], v[70:73]
	s_setprio 0
	v_mfma_f32_16x16x32_bf16 v[66:69], v[182:185], v[224:227], v[66:69]
	s_barrier
	s_add_i32 s9, s9, s29
	v_lshl_add_u64 v[148:149], s[6:7], 0, v[142:143]
	s_mov_b32 m0, s9
	ds_read_b128 v[196:199], v193 offset:16384
	ds_read_b128 v[200:203], v193 offset:17408
	ds_read_b128 v[204:207], v193 offset:18432
	ds_read_b128 v[208:211], v193 offset:19456
	ds_read_b128 v[212:215], v193 offset:20480
	ds_read_b128 v[216:219], v193 offset:21504
	ds_read_b128 v[220:223], v193 offset:22528
	ds_read_b128 v[224:227], v193 offset:23552
	global_load_lds_dwordx4 v[148:149], off
	s_add_i32 m0, s9, 0x2000
	s_add_u32 s78, s6, 0x40000
	v_lshl_add_u64 v[150:151], s[6:7], 0, v[138:139]
	s_addc_u32 s79, s7, 0
	s_add_i32 s9, s83, s29
	global_load_lds_dwordx4 v[150:151], off
	v_lshl_add_u64 v[186:187], s[78:79], 0, v[142:143]
	s_mov_b32 m0, s9
	v_lshl_add_u64 v[228:229], s[26:27], 0, v[140:141]
	global_load_lds_dwordx4 v[186:187], off
	s_add_i32 m0, s9, 0x2000
	v_lshl_add_u64 v[186:187], s[78:79], 0, v[138:139]
	global_load_lds_dwordx4 v[186:187], off
	s_mov_b32 m0, s40
	v_lshl_add_u64 v[186:187], s[26:27], 0, v[144:145]
	global_load_lds_dwordx4 v[186:187], off
	s_mov_b32 m0, s41
	s_nop 0
	global_load_lds_dwordx4 v[228:229], off
	s_waitcnt vmcnt(8) lgkmcnt(0)
	s_setprio 1
	s_barrier
	v_mfma_f32_16x16x32_bf16 v[62:65], v[130:133], v[196:199], v[62:65]
	v_mfma_f32_16x16x32_bf16 v[58:61], v[162:165], v[196:199], v[58:61]
	v_mfma_f32_16x16x32_bf16 v[54:57], v[130:133], v[204:207], v[54:57]
	v_mfma_f32_16x16x32_bf16 v[50:53], v[162:165], v[204:207], v[50:53]
	v_mfma_f32_16x16x32_bf16 v[38:41], v[130:133], v[212:215], v[38:41]
	v_mfma_f32_16x16x32_bf16 v[34:37], v[162:165], v[212:215], v[34:37]
	v_mfma_f32_16x16x32_bf16 v[22:25], v[130:133], v[220:223], v[22:25]
	v_mfma_f32_16x16x32_bf16 v[18:21], v[162:165], v[220:223], v[18:21]
	v_mfma_f32_16x16x32_bf16 v[62:65], v[134:137], v[200:203], v[62:65]
	v_mfma_f32_16x16x32_bf16 v[58:61], v[166:169], v[200:203], v[58:61]
	v_mfma_f32_16x16x32_bf16 v[54:57], v[134:137], v[208:211], v[54:57]
	v_mfma_f32_16x16x32_bf16 v[50:53], v[166:169], v[208:211], v[50:53]
	v_mfma_f32_16x16x32_bf16 v[38:41], v[134:137], v[216:219], v[38:41]
	v_mfma_f32_16x16x32_bf16 v[34:37], v[166:169], v[216:219], v[34:37]
	v_mfma_f32_16x16x32_bf16 v[22:25], v[134:137], v[224:227], v[22:25]
	v_mfma_f32_16x16x32_bf16 v[18:21], v[166:169], v[224:227], v[18:21]
	v_mfma_f32_16x16x32_bf16 v[46:49], v[170:173], v[196:199], v[46:49]
	v_mfma_f32_16x16x32_bf16 v[42:45], v[178:181], v[196:199], v[42:45]
	v_mfma_f32_16x16x32_bf16 v[30:33], v[170:173], v[204:207], v[30:33]
	v_mfma_f32_16x16x32_bf16 v[26:29], v[178:181], v[204:207], v[26:29]
	v_mfma_f32_16x16x32_bf16 v[14:17], v[170:173], v[212:215], v[14:17]
	v_mfma_f32_16x16x32_bf16 v[10:13], v[178:181], v[212:215], v[10:13]
	v_mfma_f32_16x16x32_bf16 v[6:9], v[170:173], v[220:223], v[6:9]
	v_mfma_f32_16x16x32_bf16 v[2:5], v[178:181], v[220:223], v[2:5]
	v_mfma_f32_16x16x32_bf16 v[46:49], v[174:177], v[200:203], v[46:49]
	v_mfma_f32_16x16x32_bf16 v[42:45], v[182:185], v[200:203], v[42:45]
	v_mfma_f32_16x16x32_bf16 v[30:33], v[174:177], v[208:211], v[30:33]
	v_mfma_f32_16x16x32_bf16 v[26:29], v[182:185], v[208:211], v[26:29]
	v_mfma_f32_16x16x32_bf16 v[14:17], v[174:177], v[216:219], v[14:17]
	v_mfma_f32_16x16x32_bf16 v[10:13], v[182:185], v[216:219], v[10:13]
	v_mfma_f32_16x16x32_bf16 v[6:9], v[174:177], v[224:227], v[6:9]
	s_setprio 0
	v_mfma_f32_16x16x32_bf16 v[2:5], v[182:185], v[224:227], v[2:5]
	s_barrier
	s_add_i32 s9, 0, 0x18000
	v_add_u32_e32 v0, s9, v189
	s_add_i32 s78, 0, 0x1c000
	ds_read_b128 v[130:133], v0
	ds_read_b128 v[134:137], v0 offset:1024
	ds_read_b128 v[162:165], v0 offset:2048
	ds_read_b128 v[166:169], v0 offset:3072
	v_add_u32_e32 v0, s78, v189
	ds_read_b128 v[170:173], v0
	ds_read_b128 v[174:177], v0 offset:1024
	ds_read_b128 v[178:181], v0 offset:2048
	ds_read_b128 v[182:185], v0 offset:3072
	s_add_u32 s26, s26, 0x40000
	s_addc_u32 s27, s27, 0
	s_mov_b32 m0, s42
	v_lshl_add_u64 v[230:231], s[26:27], 0, v[144:145]
	ds_read_b128 v[196:199], v193 offset:32768
	ds_read_b128 v[200:203], v193 offset:33792
	ds_read_b128 v[204:207], v193 offset:34816
	ds_read_b128 v[208:211], v193 offset:35840
	ds_read_b128 v[212:215], v193 offset:36864
	ds_read_b128 v[216:219], v193 offset:37888
	ds_read_b128 v[220:223], v193 offset:38912
	ds_read_b128 v[224:227], v193 offset:39936
	global_load_lds_dwordx4 v[230:231], off
	s_mov_b32 m0, s43
	v_lshl_add_u64 v[230:231], s[26:27], 0, v[140:141]
	global_load_lds_dwordx4 v[230:231], off
	s_waitcnt vmcnt(8) lgkmcnt(0)
	s_setprio 1
	s_barrier
	v_mfma_f32_16x16x32_bf16 v[126:129], v[130:133], v[196:199], v[126:129]
	v_mfma_f32_16x16x32_bf16 v[122:125], v[162:165], v[196:199], v[122:125]
	v_mfma_f32_16x16x32_bf16 v[118:121], v[130:133], v[204:207], v[118:121]
	v_mfma_f32_16x16x32_bf16 v[114:117], v[162:165], v[204:207], v[114:117]
	v_mfma_f32_16x16x32_bf16 v[102:105], v[130:133], v[212:215], v[102:105]
	v_mfma_f32_16x16x32_bf16 v[98:101], v[162:165], v[212:215], v[98:101]
	v_mfma_f32_16x16x32_bf16 v[86:89], v[130:133], v[220:223], v[86:89]
	v_mfma_f32_16x16x32_bf16 v[82:85], v[162:165], v[220:223], v[82:85]
	v_mfma_f32_16x16x32_bf16 v[126:129], v[134:137], v[200:203], v[126:129]
	v_mfma_f32_16x16x32_bf16 v[122:125], v[166:169], v[200:203], v[122:125]
	v_mfma_f32_16x16x32_bf16 v[118:121], v[134:137], v[208:211], v[118:121]
	v_mfma_f32_16x16x32_bf16 v[114:117], v[166:169], v[208:211], v[114:117]
	v_mfma_f32_16x16x32_bf16 v[102:105], v[134:137], v[216:219], v[102:105]
	v_mfma_f32_16x16x32_bf16 v[98:101], v[166:169], v[216:219], v[98:101]
	v_mfma_f32_16x16x32_bf16 v[86:89], v[134:137], v[224:227], v[86:89]
	v_mfma_f32_16x16x32_bf16 v[82:85], v[166:169], v[224:227], v[82:85]
	v_mfma_f32_16x16x32_bf16 v[110:113], v[170:173], v[196:199], v[110:113]
	v_mfma_f32_16x16x32_bf16 v[106:109], v[178:181], v[196:199], v[106:109]
	v_mfma_f32_16x16x32_bf16 v[94:97], v[170:173], v[204:207], v[94:97]
	v_mfma_f32_16x16x32_bf16 v[90:93], v[178:181], v[204:207], v[90:93]
	v_mfma_f32_16x16x32_bf16 v[78:81], v[170:173], v[212:215], v[78:81]
	v_mfma_f32_16x16x32_bf16 v[74:77], v[178:181], v[212:215], v[74:77]
	v_mfma_f32_16x16x32_bf16 v[70:73], v[170:173], v[220:223], v[70:73]
	v_mfma_f32_16x16x32_bf16 v[66:69], v[178:181], v[220:223], v[66:69]
	v_mfma_f32_16x16x32_bf16 v[110:113], v[174:177], v[200:203], v[110:113]
	v_mfma_f32_16x16x32_bf16 v[106:109], v[182:185], v[200:203], v[106:109]
	v_mfma_f32_16x16x32_bf16 v[94:97], v[174:177], v[208:211], v[94:97]
	v_mfma_f32_16x16x32_bf16 v[90:93], v[182:185], v[208:211], v[90:93]
	v_mfma_f32_16x16x32_bf16 v[78:81], v[174:177], v[216:219], v[78:81]
	v_mfma_f32_16x16x32_bf16 v[74:77], v[182:185], v[216:219], v[74:77]
	v_mfma_f32_16x16x32_bf16 v[70:73], v[174:177], v[224:227], v[70:73]
	s_setprio 0
	v_mfma_f32_16x16x32_bf16 v[66:69], v[182:185], v[224:227], v[66:69]
	s_barrier
	s_add_i32 s9, s9, s29
	v_lshl_add_u64 v[148:149], v[148:149], 0, s[70:71]
	s_mov_b32 m0, s9
	ds_read_b128 v[196:199], v193 offset:49152
	ds_read_b128 v[200:203], v193 offset:50176
	ds_read_b128 v[204:207], v193 offset:51200
	ds_read_b128 v[208:211], v193 offset:52224
	ds_read_b128 v[212:215], v193 offset:53248
	ds_read_b128 v[216:219], v193 offset:54272
	ds_read_b128 v[220:223], v193 offset:55296
	ds_read_b128 v[224:227], v193 offset:56320
	global_load_lds_dwordx4 v[148:149], off
	s_add_i32 m0, s9, 0x2000
	s_add_u32 s6, s6, 0x40080
	v_lshl_add_u64 v[148:149], v[150:151], 0, s[70:71]
	s_addc_u32 s7, s7, 0
	s_add_i32 s9, s78, s29
	global_load_lds_dwordx4 v[148:149], off
	s_mov_b32 m0, s9
	v_lshl_add_u64 v[148:149], s[6:7], 0, v[142:143]
	global_load_lds_dwordx4 v[148:149], off
	s_add_i32 m0, s9, 0x2000
	v_lshl_add_u64 v[148:149], s[6:7], 0, v[138:139]
	global_load_lds_dwordx4 v[148:149], off
	s_mov_b32 m0, s44
	v_lshl_add_u64 v[148:149], v[186:187], 0, s[70:71]
	global_load_lds_dwordx4 v[148:149], off
	s_mov_b32 m0, s45
	v_lshl_add_u64 v[148:149], v[228:229], 0, s[70:71]
	global_load_lds_dwordx4 v[148:149], off
	s_waitcnt vmcnt(8) lgkmcnt(0)
	s_setprio 1
	s_barrier
	v_mfma_f32_16x16x32_bf16 v[62:65], v[130:133], v[196:199], v[62:65]
	v_mfma_f32_16x16x32_bf16 v[58:61], v[162:165], v[196:199], v[58:61]
	v_mfma_f32_16x16x32_bf16 v[54:57], v[130:133], v[204:207], v[54:57]
	v_mfma_f32_16x16x32_bf16 v[50:53], v[162:165], v[204:207], v[50:53]
	v_mfma_f32_16x16x32_bf16 v[38:41], v[130:133], v[212:215], v[38:41]
	v_mfma_f32_16x16x32_bf16 v[34:37], v[162:165], v[212:215], v[34:37]
	v_mfma_f32_16x16x32_bf16 v[22:25], v[130:133], v[220:223], v[22:25]
	v_mfma_f32_16x16x32_bf16 v[18:21], v[162:165], v[220:223], v[18:21]
	v_mfma_f32_16x16x32_bf16 v[62:65], v[134:137], v[200:203], v[62:65]
	v_mfma_f32_16x16x32_bf16 v[58:61], v[166:169], v[200:203], v[58:61]
	v_mfma_f32_16x16x32_bf16 v[54:57], v[134:137], v[208:211], v[54:57]
	v_mfma_f32_16x16x32_bf16 v[50:53], v[166:169], v[208:211], v[50:53]
	v_mfma_f32_16x16x32_bf16 v[38:41], v[134:137], v[216:219], v[38:41]
	v_mfma_f32_16x16x32_bf16 v[34:37], v[166:169], v[216:219], v[34:37]
	v_mfma_f32_16x16x32_bf16 v[22:25], v[134:137], v[224:227], v[22:25]
	v_mfma_f32_16x16x32_bf16 v[18:21], v[166:169], v[224:227], v[18:21]
	v_mfma_f32_16x16x32_bf16 v[46:49], v[170:173], v[196:199], v[46:49]
	v_mfma_f32_16x16x32_bf16 v[42:45], v[178:181], v[196:199], v[42:45]
	v_mfma_f32_16x16x32_bf16 v[30:33], v[170:173], v[204:207], v[30:33]
	v_mfma_f32_16x16x32_bf16 v[26:29], v[178:181], v[204:207], v[26:29]
	v_mfma_f32_16x16x32_bf16 v[14:17], v[170:173], v[212:215], v[14:17]
	v_mfma_f32_16x16x32_bf16 v[10:13], v[178:181], v[212:215], v[10:13]
	v_mfma_f32_16x16x32_bf16 v[6:9], v[170:173], v[220:223], v[6:9]
	v_mfma_f32_16x16x32_bf16 v[2:5], v[178:181], v[220:223], v[2:5]
	v_mfma_f32_16x16x32_bf16 v[46:49], v[174:177], v[200:203], v[46:49]
	v_mfma_f32_16x16x32_bf16 v[42:45], v[182:185], v[200:203], v[42:45]
	v_mfma_f32_16x16x32_bf16 v[30:33], v[174:177], v[208:211], v[30:33]
	v_mfma_f32_16x16x32_bf16 v[26:29], v[182:185], v[208:211], v[26:29]
	v_mfma_f32_16x16x32_bf16 v[14:17], v[174:177], v[216:219], v[14:17]
	v_mfma_f32_16x16x32_bf16 v[10:13], v[182:185], v[216:219], v[10:13]
	v_mfma_f32_16x16x32_bf16 v[6:9], v[174:177], v[224:227], v[6:9]
	s_setprio 0
	v_mfma_f32_16x16x32_bf16 v[2:5], v[182:185], v[224:227], v[2:5]
	s_barrier
	s_add_i32 s53, s53, 2
	s_add_u32 s4, s4, 0x100
	s_addc_u32 s5, s5, 0
	s_add_u32 s51, s51, 0x100
	s_addc_u32 s52, s52, 0
	s_cmp_gt_u32 s53, 13
	s_cbranch_scc0 .LBB0_182
	s_and_b64 vcc, exec, s[36:37]
	s_cbranch_vccz .LBB0_185
	s_barrier

.LBB0_220:
	s_add_u32 s9, s36, 0xfffc0080
	s_addc_u32 s26, s37, -1
	s_add_i32 s60, 0, 0x10000
	s_cmp_eq_u32 s53, 12
	s_cselect_b32 s39, s19, s26
	s_cselect_b32 s38, s49, s9
	v_add_u32_e32 v148, s60, v141
	s_cselect_b32 s27, s17, s52
	s_cselect_b32 s26, s50, s51
	s_add_i32 s9, 0, 0x14000
	ds_read_b128 v[144:147], v148
	ds_read_b128 v[156:159], v148 offset:1024
	ds_read_b128 v[160:163], v148 offset:2048
	ds_read_b128 v[164:167], v148 offset:3072
	v_add_u32_e32 v148, s9, v141
	ds_read_b128 v[168:171], v148
	ds_read_b128 v[172:175], v148 offset:1024
	ds_read_b128 v[176:179], v148 offset:2048
	ds_read_b128 v[180:183], v148 offset:3072
	v_lshl_add_u64 v[148:149], s[36:37], 0, v[136:137]
	s_add_i32 m0, s40, 0xc000
	ds_read_b128 v[184:187], v143
	ds_read_b128 v[188:191], v143 offset:1024
	ds_read_b128 v[192:195], v143 offset:2048
	ds_read_b128 v[196:199], v143 offset:3072
	ds_read_b128 v[200:203], v143 offset:4096
	ds_read_b128 v[204:207], v143 offset:5120
	ds_read_b128 v[208:211], v143 offset:6144
	ds_read_b128 v[212:215], v143 offset:7168
	global_load_lds_dwordx4 v[148:149], off
	s_add_i32 m0, s40, 0xe000
	v_lshl_add_u64 v[148:149], s[36:37], 0, v[138:139]
	global_load_lds_dwordx4 v[148:149], off
	s_waitcnt vmcnt(8) lgkmcnt(0)
	s_setprio 1
	s_barrier
	v_mfma_f32_16x16x32_bf16 v[126:129], v[144:147], v[184:187], v[126:129]
	v_mfma_f32_16x16x32_bf16 v[122:125], v[160:163], v[184:187], v[122:125]
	v_mfma_f32_16x16x32_bf16 v[118:121], v[144:147], v[192:195], v[118:121]
	v_mfma_f32_16x16x32_bf16 v[114:117], v[160:163], v[192:195], v[114:117]
	v_mfma_f32_16x16x32_bf16 v[102:105], v[144:147], v[200:203], v[102:105]
	v_mfma_f32_16x16x32_bf16 v[98:101], v[160:163], v[200:203], v[98:101]
	v_mfma_f32_16x16x32_bf16 v[86:89], v[144:147], v[208:211], v[86:89]
	v_mfma_f32_16x16x32_bf16 v[82:85], v[160:163], v[208:211], v[82:85]
	v_mfma_f32_16x16x32_bf16 v[126:129], v[156:159], v[188:191], v[126:129]
	v_mfma_f32_16x16x32_bf16 v[122:125], v[164:167], v[188:191], v[122:125]
	v_mfma_f32_16x16x32_bf16 v[118:121], v[156:159], v[196:199], v[118:121]
	v_mfma_f32_16x16x32_bf16 v[114:117], v[164:167], v[196:199], v[114:117]
	v_mfma_f32_16x16x32_bf16 v[102:105], v[156:159], v[204:207], v[102:105]
	v_mfma_f32_16x16x32_bf16 v[98:101], v[164:167], v[204:207], v[98:101]
	v_mfma_f32_16x16x32_bf16 v[86:89], v[156:159], v[212:215], v[86:89]
	v_mfma_f32_16x16x32_bf16 v[82:85], v[164:167], v[212:215], v[82:85]
	v_mfma_f32_16x16x32_bf16 v[110:113], v[168:171], v[184:187], v[110:113]
	v_mfma_f32_16x16x32_bf16 v[106:109], v[176:179], v[184:187], v[106:109]
	v_mfma_f32_16x16x32_bf16 v[94:97], v[168:171], v[192:195], v[94:97]
	v_mfma_f32_16x16x32_bf16 v[90:93], v[176:179], v[192:195], v[90:93]
	v_mfma_f32_16x16x32_bf16 v[78:81], v[168:171], v[200:203], v[78:81]
	v_mfma_f32_16x16x32_bf16 v[74:77], v[176:179], v[200:203], v[74:77]
	v_mfma_f32_16x16x32_bf16 v[70:73], v[168:171], v[208:211], v[70:73]
	v_mfma_f32_16x16x32_bf16 v[66:69], v[176:179], v[208:211], v[66:69]
	v_mfma_f32_16x16x32_bf16 v[110:113], v[172:175], v[188:191], v[110:113]
	v_mfma_f32_16x16x32_bf16 v[106:109], v[180:183], v[188:191], v[106:109]
	v_mfma_f32_16x16x32_bf16 v[94:97], v[172:175], v[196:199], v[94:97]
	v_mfma_f32_16x16x32_bf16 v[90:93], v[180:183], v[196:199], v[90:93]
	v_mfma_f32_16x16x32_bf16 v[78:81], v[172:175], v[204:207], v[78:81]
	v_mfma_f32_16x16x32_bf16 v[74:77], v[180:183], v[204:207], v[74:77]
	v_mfma_f32_16x16x32_bf16 v[70:73], v[172:175], v[212:215], v[70:73]
	s_setprio 0
	v_mfma_f32_16x16x32_bf16 v[66:69], v[180:183], v[212:215], v[66:69]
	s_barrier
	s_add_i32 s60, s60, s29
	v_lshl_add_u64 v[148:149], s[26:27], 0, v[0:1]
	s_mov_b32 m0, s60
	ds_read_b128 v[184:187], v143 offset:16384
	ds_read_b128 v[188:191], v143 offset:17408
	ds_read_b128 v[192:195], v143 offset:18432
	ds_read_b128 v[196:199], v143 offset:19456
	ds_read_b128 v[200:203], v143 offset:20480
	ds_read_b128 v[204:207], v143 offset:21504
	ds_read_b128 v[208:211], v143 offset:22528
	ds_read_b128 v[212:215], v143 offset:23552
	global_load_lds_dwordx4 v[148:149], off
	s_add_i32 m0, s60, 0x2000
	s_add_u32 s60, s26, 0x40000
	v_lshl_add_u64 v[150:151], s[26:27], 0, v[130:131]
	s_addc_u32 s61, s27, 0
	s_add_i32 s9, s9, s29
	global_load_lds_dwordx4 v[150:151], off
	v_lshl_add_u64 v[216:217], s[60:61], 0, v[0:1]
	s_mov_b32 m0, s9
	v_lshl_add_u64 v[218:219], s[38:39], 0, v[132:133]
	global_load_lds_dwordx4 v[216:217], off
	s_add_i32 m0, s9, 0x2000
	v_lshl_add_u64 v[216:217], s[60:61], 0, v[130:131]
	global_load_lds_dwordx4 v[216:217], off
	s_mov_b32 m0, s40
	v_lshl_add_u64 v[216:217], s[38:39], 0, v[134:135]
	global_load_lds_dwordx4 v[216:217], off
	s_mov_b32 m0, s41
	s_nop 0
	global_load_lds_dwordx4 v[218:219], off
	s_waitcnt vmcnt(8) lgkmcnt(0)
	s_setprio 1
	s_barrier
	v_mfma_f32_16x16x32_bf16 v[62:65], v[144:147], v[184:187], v[62:65]
	v_mfma_f32_16x16x32_bf16 v[58:61], v[160:163], v[184:187], v[58:61]
	v_mfma_f32_16x16x32_bf16 v[54:57], v[144:147], v[192:195], v[54:57]
	v_mfma_f32_16x16x32_bf16 v[50:53], v[160:163], v[192:195], v[50:53]
	v_mfma_f32_16x16x32_bf16 v[38:41], v[144:147], v[200:203], v[38:41]
	v_mfma_f32_16x16x32_bf16 v[34:37], v[160:163], v[200:203], v[34:37]
	v_mfma_f32_16x16x32_bf16 v[22:25], v[144:147], v[208:211], v[22:25]
	v_mfma_f32_16x16x32_bf16 v[18:21], v[160:163], v[208:211], v[18:21]
	v_mfma_f32_16x16x32_bf16 v[62:65], v[156:159], v[188:191], v[62:65]
	v_mfma_f32_16x16x32_bf16 v[58:61], v[164:167], v[188:191], v[58:61]
	v_mfma_f32_16x16x32_bf16 v[54:57], v[156:159], v[196:199], v[54:57]
	v_mfma_f32_16x16x32_bf16 v[50:53], v[164:167], v[196:199], v[50:53]
	v_mfma_f32_16x16x32_bf16 v[38:41], v[156:159], v[204:207], v[38:41]
	v_mfma_f32_16x16x32_bf16 v[34:37], v[164:167], v[204:207], v[34:37]
	v_mfma_f32_16x16x32_bf16 v[22:25], v[156:159], v[212:215], v[22:25]
	v_mfma_f32_16x16x32_bf16 v[18:21], v[164:167], v[212:215], v[18:21]
	v_mfma_f32_16x16x32_bf16 v[46:49], v[168:171], v[184:187], v[46:49]
	v_mfma_f32_16x16x32_bf16 v[42:45], v[176:179], v[184:187], v[42:45]
	v_mfma_f32_16x16x32_bf16 v[30:33], v[168:171], v[192:195], v[30:33]
	v_mfma_f32_16x16x32_bf16 v[26:29], v[176:179], v[192:195], v[26:29]
	v_mfma_f32_16x16x32_bf16 v[14:17], v[168:171], v[200:203], v[14:17]
	v_mfma_f32_16x16x32_bf16 v[10:13], v[176:179], v[200:203], v[10:13]
	v_mfma_f32_16x16x32_bf16 v[6:9], v[168:171], v[208:211], v[6:9]
	v_mfma_f32_16x16x32_bf16 v[2:5], v[176:179], v[208:211], v[2:5]
	v_mfma_f32_16x16x32_bf16 v[46:49], v[172:175], v[188:191], v[46:49]
	v_mfma_f32_16x16x32_bf16 v[42:45], v[180:183], v[188:191], v[42:45]
	v_mfma_f32_16x16x32_bf16 v[30:33], v[172:175], v[196:199], v[30:33]
	v_mfma_f32_16x16x32_bf16 v[26:29], v[180:183], v[196:199], v[26:29]
	v_mfma_f32_16x16x32_bf16 v[14:17], v[172:175], v[204:207], v[14:17]
	v_mfma_f32_16x16x32_bf16 v[10:13], v[180:183], v[204:207], v[10:13]
	v_mfma_f32_16x16x32_bf16 v[6:9], v[172:175], v[212:215], v[6:9]
	s_setprio 0
	v_mfma_f32_16x16x32_bf16 v[2:5], v[180:183], v[212:215], v[2:5]
	s_barrier
	s_add_i32 s9, 0, 0x18000
	s_add_i32 s60, 0, 0x1c000
	v_add_u32_e32 v164, s9, v141
	v_add_u32_e32 v180, s60, v141
	ds_read_b128 v[144:147], v164
	ds_read_b128 v[156:159], v164 offset:1024
	ds_read_b128 v[160:163], v164 offset:2048
	ds_read_b128 v[164:167], v164 offset:3072
	ds_read_b128 v[168:171], v180
	ds_read_b128 v[172:175], v180 offset:1024
	ds_read_b128 v[176:179], v180 offset:2048
	ds_read_b128 v[180:183], v180 offset:3072
	s_add_u32 s38, s38, 0x40000
	s_addc_u32 s39, s39, 0
	s_mov_b32 m0, s42
	v_lshl_add_u64 v[220:221], s[38:39], 0, v[134:135]
	ds_read_b128 v[184:187], v143 offset:32768
	ds_read_b128 v[188:191], v143 offset:33792
	ds_read_b128 v[192:195], v143 offset:34816
	ds_read_b128 v[196:199], v143 offset:35840
	ds_read_b128 v[200:203], v143 offset:36864
	ds_read_b128 v[204:207], v143 offset:37888
	ds_read_b128 v[208:211], v143 offset:38912
	ds_read_b128 v[212:215], v143 offset:39936
	global_load_lds_dwordx4 v[220:221], off
	s_mov_b32 m0, s43
	v_lshl_add_u64 v[220:221], s[38:39], 0, v[132:133]
	global_load_lds_dwordx4 v[220:221], off
	s_waitcnt vmcnt(8) lgkmcnt(0)
	s_setprio 1
	s_barrier
	v_mfma_f32_16x16x32_bf16 v[126:129], v[144:147], v[184:187], v[126:129]
	v_mfma_f32_16x16x32_bf16 v[122:125], v[160:163], v[184:187], v[122:125]
	v_mfma_f32_16x16x32_bf16 v[118:121], v[144:147], v[192:195], v[118:121]
	v_mfma_f32_16x16x32_bf16 v[114:117], v[160:163], v[192:195], v[114:117]
	v_mfma_f32_16x16x32_bf16 v[102:105], v[144:147], v[200:203], v[102:105]
	v_mfma_f32_16x16x32_bf16 v[98:101], v[160:163], v[200:203], v[98:101]
	v_mfma_f32_16x16x32_bf16 v[86:89], v[144:147], v[208:211], v[86:89]
	v_mfma_f32_16x16x32_bf16 v[82:85], v[160:163], v[208:211], v[82:85]
	v_mfma_f32_16x16x32_bf16 v[126:129], v[156:159], v[188:191], v[126:129]
	v_mfma_f32_16x16x32_bf16 v[122:125], v[164:167], v[188:191], v[122:125]
	v_mfma_f32_16x16x32_bf16 v[118:121], v[156:159], v[196:199], v[118:121]
	v_mfma_f32_16x16x32_bf16 v[114:117], v[164:167], v[196:199], v[114:117]
	v_mfma_f32_16x16x32_bf16 v[102:105], v[156:159], v[204:207], v[102:105]
	v_mfma_f32_16x16x32_bf16 v[98:101], v[164:167], v[204:207], v[98:101]
	v_mfma_f32_16x16x32_bf16 v[86:89], v[156:159], v[212:215], v[86:89]
	v_mfma_f32_16x16x32_bf16 v[82:85], v[164:167], v[212:215], v[82:85]
	v_mfma_f32_16x16x32_bf16 v[110:113], v[168:171], v[184:187], v[110:113]
	v_mfma_f32_16x16x32_bf16 v[106:109], v[176:179], v[184:187], v[106:109]
	v_mfma_f32_16x16x32_bf16 v[94:97], v[168:171], v[192:195], v[94:97]
	v_mfma_f32_16x16x32_bf16 v[90:93], v[176:179], v[192:195], v[90:93]
	v_mfma_f32_16x16x32_bf16 v[78:81], v[168:171], v[200:203], v[78:81]
	v_mfma_f32_16x16x32_bf16 v[74:77], v[176:179], v[200:203], v[74:77]
	v_mfma_f32_16x16x32_bf16 v[70:73], v[168:171], v[208:211], v[70:73]
	v_mfma_f32_16x16x32_bf16 v[66:69], v[176:179], v[208:211], v[66:69]
	v_mfma_f32_16x16x32_bf16 v[110:113], v[172:175], v[188:191], v[110:113]
	v_mfma_f32_16x16x32_bf16 v[106:109], v[180:183], v[188:191], v[106:109]
	v_mfma_f32_16x16x32_bf16 v[94:97], v[172:175], v[196:199], v[94:97]
	v_mfma_f32_16x16x32_bf16 v[90:93], v[180:183], v[196:199], v[90:93]
	v_mfma_f32_16x16x32_bf16 v[78:81], v[172:175], v[204:207], v[78:81]
	v_mfma_f32_16x16x32_bf16 v[74:77], v[180:183], v[204:207], v[74:77]
	v_mfma_f32_16x16x32_bf16 v[70:73], v[172:175], v[212:215], v[70:73]
	s_setprio 0
	v_mfma_f32_16x16x32_bf16 v[66:69], v[180:183], v[212:215], v[66:69]
	s_barrier
	s_add_i32 s9, s9, s29
	v_lshl_add_u64 v[148:149], v[148:149], 0, s[70:71]
	s_mov_b32 m0, s9
	ds_read_b128 v[184:187], v143 offset:49152
	ds_read_b128 v[188:191], v143 offset:50176
	ds_read_b128 v[192:195], v143 offset:51200
	ds_read_b128 v[196:199], v143 offset:52224
	ds_read_b128 v[200:203], v143 offset:53248
	ds_read_b128 v[204:207], v143 offset:54272
	ds_read_b128 v[208:211], v143 offset:55296
	ds_read_b128 v[212:215], v143 offset:56320
	global_load_lds_dwordx4 v[148:149], off
	s_add_i32 m0, s9, 0x2000
	s_add_u32 s26, s26, 0x40080
	v_lshl_add_u64 v[148:149], v[150:151], 0, s[70:71]
	s_addc_u32 s27, s27, 0
	s_add_i32 s9, s60, s29
	global_load_lds_dwordx4 v[148:149], off
	s_mov_b32 m0, s9
	v_lshl_add_u64 v[148:149], s[26:27], 0, v[0:1]
	global_load_lds_dwordx4 v[148:149], off
	s_add_i32 m0, s9, 0x2000
	v_lshl_add_u64 v[148:149], s[26:27], 0, v[130:131]
	global_load_lds_dwordx4 v[148:149], off
	s_mov_b32 m0, s44
	v_lshl_add_u64 v[148:149], v[216:217], 0, s[70:71]
	global_load_lds_dwordx4 v[148:149], off
	s_mov_b32 m0, s45
	v_lshl_add_u64 v[148:149], v[218:219], 0, s[70:71]
	global_load_lds_dwordx4 v[148:149], off
	s_waitcnt vmcnt(8) lgkmcnt(0)
	s_setprio 1
	s_barrier
	v_mfma_f32_16x16x32_bf16 v[62:65], v[144:147], v[184:187], v[62:65]
	v_mfma_f32_16x16x32_bf16 v[58:61], v[160:163], v[184:187], v[58:61]
	v_mfma_f32_16x16x32_bf16 v[54:57], v[144:147], v[192:195], v[54:57]
	v_mfma_f32_16x16x32_bf16 v[50:53], v[160:163], v[192:195], v[50:53]
	v_mfma_f32_16x16x32_bf16 v[38:41], v[144:147], v[200:203], v[38:41]
	v_mfma_f32_16x16x32_bf16 v[34:37], v[160:163], v[200:203], v[34:37]
	v_mfma_f32_16x16x32_bf16 v[22:25], v[144:147], v[208:211], v[22:25]
	v_mfma_f32_16x16x32_bf16 v[18:21], v[160:163], v[208:211], v[18:21]
	v_mfma_f32_16x16x32_bf16 v[62:65], v[156:159], v[188:191], v[62:65]
	v_mfma_f32_16x16x32_bf16 v[58:61], v[164:167], v[188:191], v[58:61]
	v_mfma_f32_16x16x32_bf16 v[54:57], v[156:159], v[196:199], v[54:57]
	v_mfma_f32_16x16x32_bf16 v[50:53], v[164:167], v[196:199], v[50:53]
	v_mfma_f32_16x16x32_bf16 v[38:41], v[156:159], v[204:207], v[38:41]
	v_mfma_f32_16x16x32_bf16 v[34:37], v[164:167], v[204:207], v[34:37]
	v_mfma_f32_16x16x32_bf16 v[22:25], v[156:159], v[212:215], v[22:25]
	v_mfma_f32_16x16x32_bf16 v[18:21], v[164:167], v[212:215], v[18:21]
	v_mfma_f32_16x16x32_bf16 v[46:49], v[168:171], v[184:187], v[46:49]
	v_mfma_f32_16x16x32_bf16 v[42:45], v[176:179], v[184:187], v[42:45]
	v_mfma_f32_16x16x32_bf16 v[30:33], v[168:171], v[192:195], v[30:33]
	v_mfma_f32_16x16x32_bf16 v[26:29], v[176:179], v[192:195], v[26:29]
	v_mfma_f32_16x16x32_bf16 v[14:17], v[168:171], v[200:203], v[14:17]
	v_mfma_f32_16x16x32_bf16 v[10:13], v[176:179], v[200:203], v[10:13]
	v_mfma_f32_16x16x32_bf16 v[6:9], v[168:171], v[208:211], v[6:9]
	v_mfma_f32_16x16x32_bf16 v[2:5], v[176:179], v[208:211], v[2:5]
	v_mfma_f32_16x16x32_bf16 v[46:49], v[172:175], v[188:191], v[46:49]
	v_mfma_f32_16x16x32_bf16 v[42:45], v[180:183], v[188:191], v[42:45]
	v_mfma_f32_16x16x32_bf16 v[30:33], v[172:175], v[196:199], v[30:33]
	v_mfma_f32_16x16x32_bf16 v[26:29], v[180:183], v[196:199], v[26:29]
	v_mfma_f32_16x16x32_bf16 v[14:17], v[172:175], v[204:207], v[14:17]
	v_mfma_f32_16x16x32_bf16 v[10:13], v[180:183], v[204:207], v[10:13]
	v_mfma_f32_16x16x32_bf16 v[6:9], v[172:175], v[212:215], v[6:9]
	s_setprio 0
	v_mfma_f32_16x16x32_bf16 v[2:5], v[180:183], v[212:215], v[2:5]
	s_barrier
	s_add_i32 s53, s53, 2
	s_add_u32 s36, s36, 0x100
	s_addc_u32 s37, s37, 0
	s_add_u32 s51, s51, 0x100
	s_addc_u32 s52, s52, 0
	s_cmp_gt_u32 s53, 13
	s_cbranch_scc0 .LBB0_220
	s_and_b64 vcc, exec, s[14:15]
	s_cbranch_vccz .LBB0_223
	s_barrier

.LBB0_376:
	s_add_u32 s53, s18, s9
	s_addc_u32 s74, s19, 0
	s_add_u32 s60, s53, 0x100
	s_addc_u32 s61, s74, 0
	s_and_b64 s[26:27], s[38:39], exec
	s_cselect_b32 s61, s25, s61
	s_cselect_b32 s60, s24, s60
	s_add_u32 s9, s16, s9
	s_addc_u32 s26, s17, 0
	s_add_u32 s9, s9, 0x100
	s_addc_u32 s72, s26, 0
	s_add_i32 s92, 0, 0x10000
	s_and_b64 s[26:27], s[38:39], exec
	s_cselect_b32 s73, s23, s72
	s_cselect_b32 s72, s52, s9
	s_add_i32 s39, 0, 0x14000
	s_add_u32 vcc_lo, s53, 0x58080
	s_addc_u32 vcc_hi, s74, 0
	s_add_i32 s78, s92, s41
	s_add_i32 m0, s42, 0xc000
	s_add_i32 s93, s42, 0xe000
	s_add_i32 s91, s78, 0x2000
	v_add_u32_e32 v148, s92, v137
	s_add_u32 s74, s72, 0x10000
	ds_read_b128 v[140:143], v148
	ds_read_b128 v[144:147], v148 offset:1024
	ds_read_b128 v[156:159], v148 offset:2048
	ds_read_b128 v[160:163], v148 offset:3072
	v_add_u32_e32 v148, s39, v137
	s_addc_u32 s75, s73, 0
	s_add_i32 s79, s39, s41
	ds_read_b128 v[164:167], v148
	ds_read_b128 v[168:171], v148 offset:1024
	ds_read_b128 v[172:175], v148 offset:2048
	ds_read_b128 v[176:179], v148 offset:3072
	s_add_i32 s90, s79, 0x2000
	s_add_i32 s97, 0, 0x18000
	s_add_i32 s83, 0, 0x1c000
	s_add_u32 s26, s60, 0x58000
	s_addc_u32 s27, s61, 0
	s_add_i32 s53, s97, s41
	s_add_i32 s9, s53, 0x2000
	s_add_u32 s38, s72, 0x10080
	s_addc_u32 s39, s73, 0
	s_add_i32 s96, s83, s41
	s_add_i32 s92, s96, 0x2000
	v_lshl_add_u64 v[148:149], vcc, 0, v[134:135]
	ds_read_b128 v[180:183], v139
	ds_read_b128 v[184:187], v139 offset:1024
	ds_read_b128 v[188:191], v139 offset:2048
	ds_read_b128 v[192:195], v139 offset:3072
	ds_read_b128 v[196:199], v139 offset:4096
	ds_read_b128 v[200:203], v139 offset:5120
	ds_read_b128 v[204:207], v139 offset:6144
	ds_read_b128 v[208:211], v139 offset:7168
	global_load_lds_dwordx4 v[148:149], off
	s_mov_b32 m0, s93
	v_lshl_add_u64 v[148:149], vcc, 0, v[132:133]
	global_load_lds_dwordx4 v[148:149], off
	s_waitcnt vmcnt(8) lgkmcnt(0)
	s_setprio 1
	s_barrier
	v_mfma_f32_16x16x32_bf16 v[126:129], v[140:143], v[180:183], v[126:129]
	v_mfma_f32_16x16x32_bf16 v[122:125], v[156:159], v[180:183], v[122:125]
	v_mfma_f32_16x16x32_bf16 v[118:121], v[140:143], v[188:191], v[118:121]
	v_mfma_f32_16x16x32_bf16 v[114:117], v[156:159], v[188:191], v[114:117]
	v_mfma_f32_16x16x32_bf16 v[102:105], v[140:143], v[196:199], v[102:105]
	v_mfma_f32_16x16x32_bf16 v[98:101], v[156:159], v[196:199], v[98:101]
	v_mfma_f32_16x16x32_bf16 v[86:89], v[140:143], v[204:207], v[86:89]
	v_mfma_f32_16x16x32_bf16 v[82:85], v[156:159], v[204:207], v[82:85]
	v_mfma_f32_16x16x32_bf16 v[126:129], v[144:147], v[184:187], v[126:129]
	v_mfma_f32_16x16x32_bf16 v[122:125], v[160:163], v[184:187], v[122:125]
	v_mfma_f32_16x16x32_bf16 v[118:121], v[144:147], v[192:195], v[118:121]
	v_mfma_f32_16x16x32_bf16 v[114:117], v[160:163], v[192:195], v[114:117]
	v_mfma_f32_16x16x32_bf16 v[102:105], v[144:147], v[200:203], v[102:105]
	v_mfma_f32_16x16x32_bf16 v[98:101], v[160:163], v[200:203], v[98:101]
	v_mfma_f32_16x16x32_bf16 v[86:89], v[144:147], v[208:211], v[86:89]
	v_mfma_f32_16x16x32_bf16 v[82:85], v[160:163], v[208:211], v[82:85]
	v_mfma_f32_16x16x32_bf16 v[110:113], v[164:167], v[180:183], v[110:113]
	v_mfma_f32_16x16x32_bf16 v[106:109], v[172:175], v[180:183], v[106:109]
	v_mfma_f32_16x16x32_bf16 v[94:97], v[164:167], v[188:191], v[94:97]
	v_mfma_f32_16x16x32_bf16 v[90:93], v[172:175], v[188:191], v[90:93]
	v_mfma_f32_16x16x32_bf16 v[78:81], v[164:167], v[196:199], v[78:81]
	v_mfma_f32_16x16x32_bf16 v[74:77], v[172:175], v[196:199], v[74:77]
	v_mfma_f32_16x16x32_bf16 v[70:73], v[164:167], v[204:207], v[70:73]
	v_mfma_f32_16x16x32_bf16 v[66:69], v[172:175], v[204:207], v[66:69]
	v_mfma_f32_16x16x32_bf16 v[110:113], v[168:171], v[184:187], v[110:113]
	v_mfma_f32_16x16x32_bf16 v[106:109], v[176:179], v[184:187], v[106:109]
	v_mfma_f32_16x16x32_bf16 v[94:97], v[168:171], v[192:195], v[94:97]
	v_mfma_f32_16x16x32_bf16 v[90:93], v[176:179], v[192:195], v[90:93]
	v_mfma_f32_16x16x32_bf16 v[78:81], v[168:171], v[200:203], v[78:81]
	v_mfma_f32_16x16x32_bf16 v[74:77], v[176:179], v[200:203], v[74:77]
	v_mfma_f32_16x16x32_bf16 v[70:73], v[168:171], v[208:211], v[70:73]
	s_setprio 0
	v_mfma_f32_16x16x32_bf16 v[66:69], v[176:179], v[208:211], v[66:69]
	s_barrier
	s_mov_b32 m0, s78
	v_lshl_add_u64 v[148:149], s[72:73], 0, v[0:1]
	ds_read_b128 v[180:183], v139 offset:16384
	ds_read_b128 v[184:187], v139 offset:17408
	ds_read_b128 v[188:191], v139 offset:18432
	ds_read_b128 v[192:195], v139 offset:19456
	ds_read_b128 v[196:199], v139 offset:20480
	ds_read_b128 v[200:203], v139 offset:21504
	ds_read_b128 v[204:207], v139 offset:22528
	ds_read_b128 v[208:211], v139 offset:23552
	global_load_lds_dwordx4 v[148:149], off
	v_lshl_add_u64 v[150:151], s[72:73], 0, v[130:131]
	s_mov_b32 m0, s91
	v_lshl_add_u64 v[212:213], s[74:75], 0, v[0:1]
	global_load_lds_dwordx4 v[150:151], off
	s_mov_b32 m0, s79
	v_lshl_add_u64 v[214:215], s[60:61], 0, v[132:133]
	global_load_lds_dwordx4 v[212:213], off
	s_mov_b32 m0, s90
	v_lshl_add_u64 v[212:213], s[74:75], 0, v[130:131]
	global_load_lds_dwordx4 v[212:213], off
	s_mov_b32 m0, s42
	v_lshl_add_u64 v[212:213], s[60:61], 0, v[134:135]
	global_load_lds_dwordx4 v[212:213], off
	s_mov_b32 m0, s43
	s_nop 0
	global_load_lds_dwordx4 v[214:215], off
	s_waitcnt vmcnt(8) lgkmcnt(0)
	s_setprio 1
	s_barrier
	v_mfma_f32_16x16x32_bf16 v[62:65], v[140:143], v[180:183], v[62:65]
	v_mfma_f32_16x16x32_bf16 v[58:61], v[156:159], v[180:183], v[58:61]
	v_mfma_f32_16x16x32_bf16 v[54:57], v[140:143], v[188:191], v[54:57]
	v_mfma_f32_16x16x32_bf16 v[50:53], v[156:159], v[188:191], v[50:53]
	v_mfma_f32_16x16x32_bf16 v[38:41], v[140:143], v[196:199], v[38:41]
	v_mfma_f32_16x16x32_bf16 v[34:37], v[156:159], v[196:199], v[34:37]
	v_mfma_f32_16x16x32_bf16 v[22:25], v[140:143], v[204:207], v[22:25]
	v_mfma_f32_16x16x32_bf16 v[18:21], v[156:159], v[204:207], v[18:21]
	v_mfma_f32_16x16x32_bf16 v[62:65], v[144:147], v[184:187], v[62:65]
	v_mfma_f32_16x16x32_bf16 v[58:61], v[160:163], v[184:187], v[58:61]
	v_mfma_f32_16x16x32_bf16 v[54:57], v[144:147], v[192:195], v[54:57]
	v_mfma_f32_16x16x32_bf16 v[50:53], v[160:163], v[192:195], v[50:53]
	v_mfma_f32_16x16x32_bf16 v[38:41], v[144:147], v[200:203], v[38:41]
	v_mfma_f32_16x16x32_bf16 v[34:37], v[160:163], v[200:203], v[34:37]
	v_mfma_f32_16x16x32_bf16 v[22:25], v[144:147], v[208:211], v[22:25]
	v_mfma_f32_16x16x32_bf16 v[18:21], v[160:163], v[208:211], v[18:21]
	v_mfma_f32_16x16x32_bf16 v[46:49], v[164:167], v[180:183], v[46:49]
	v_mfma_f32_16x16x32_bf16 v[42:45], v[172:175], v[180:183], v[42:45]
	v_mfma_f32_16x16x32_bf16 v[30:33], v[164:167], v[188:191], v[30:33]
	v_mfma_f32_16x16x32_bf16 v[26:29], v[172:175], v[188:191], v[26:29]
	v_mfma_f32_16x16x32_bf16 v[14:17], v[164:167], v[196:199], v[14:17]
	v_mfma_f32_16x16x32_bf16 v[10:13], v[172:175], v[196:199], v[10:13]
	v_mfma_f32_16x16x32_bf16 v[6:9], v[164:167], v[204:207], v[6:9]
	v_mfma_f32_16x16x32_bf16 v[2:5], v[172:175], v[204:207], v[2:5]
	v_mfma_f32_16x16x32_bf16 v[46:49], v[168:171], v[184:187], v[46:49]
	v_mfma_f32_16x16x32_bf16 v[42:45], v[176:179], v[184:187], v[42:45]
	v_mfma_f32_16x16x32_bf16 v[30:33], v[168:171], v[192:195], v[30:33]
	v_mfma_f32_16x16x32_bf16 v[26:29], v[176:179], v[192:195], v[26:29]
	v_mfma_f32_16x16x32_bf16 v[14:17], v[168:171], v[200:203], v[14:17]
	v_mfma_f32_16x16x32_bf16 v[10:13], v[176:179], v[200:203], v[10:13]
	v_mfma_f32_16x16x32_bf16 v[6:9], v[168:171], v[208:211], v[6:9]
	s_setprio 0
	v_mfma_f32_16x16x32_bf16 v[2:5], v[176:179], v[208:211], v[2:5]
	s_barrier
	v_add_u32_e32 v160, s97, v137
	v_add_u32_e32 v176, s83, v137
	ds_read_b128 v[140:143], v160
	ds_read_b128 v[144:147], v160 offset:1024
	ds_read_b128 v[156:159], v160 offset:2048
	ds_read_b128 v[160:163], v160 offset:3072
	ds_read_b128 v[164:167], v176
	ds_read_b128 v[168:171], v176 offset:1024
	ds_read_b128 v[172:175], v176 offset:2048
	ds_read_b128 v[176:179], v176 offset:3072
	s_mov_b32 m0, s44
	v_lshl_add_u64 v[216:217], s[26:27], 0, v[134:135]
	ds_read_b128 v[180:183], v139 offset:32768
	ds_read_b128 v[184:187], v139 offset:33792
	ds_read_b128 v[188:191], v139 offset:34816
	ds_read_b128 v[192:195], v139 offset:35840
	ds_read_b128 v[196:199], v139 offset:36864
	ds_read_b128 v[200:203], v139 offset:37888
	ds_read_b128 v[204:207], v139 offset:38912
	ds_read_b128 v[208:211], v139 offset:39936
	global_load_lds_dwordx4 v[216:217], off
	s_mov_b32 m0, s45
	v_lshl_add_u64 v[216:217], s[26:27], 0, v[132:133]
	global_load_lds_dwordx4 v[216:217], off
	s_waitcnt vmcnt(8) lgkmcnt(0)
	s_setprio 1
	s_barrier
	v_mfma_f32_16x16x32_bf16 v[126:129], v[140:143], v[180:183], v[126:129]
	v_mfma_f32_16x16x32_bf16 v[122:125], v[156:159], v[180:183], v[122:125]
	v_mfma_f32_16x16x32_bf16 v[118:121], v[140:143], v[188:191], v[118:121]
	v_mfma_f32_16x16x32_bf16 v[114:117], v[156:159], v[188:191], v[114:117]
	v_mfma_f32_16x16x32_bf16 v[102:105], v[140:143], v[196:199], v[102:105]
	v_mfma_f32_16x16x32_bf16 v[98:101], v[156:159], v[196:199], v[98:101]
	v_mfma_f32_16x16x32_bf16 v[86:89], v[140:143], v[204:207], v[86:89]
	v_mfma_f32_16x16x32_bf16 v[82:85], v[156:159], v[204:207], v[82:85]
	v_mfma_f32_16x16x32_bf16 v[126:129], v[144:147], v[184:187], v[126:129]
	v_mfma_f32_16x16x32_bf16 v[122:125], v[160:163], v[184:187], v[122:125]
	v_mfma_f32_16x16x32_bf16 v[118:121], v[144:147], v[192:195], v[118:121]
	v_mfma_f32_16x16x32_bf16 v[114:117], v[160:163], v[192:195], v[114:117]
	v_mfma_f32_16x16x32_bf16 v[102:105], v[144:147], v[200:203], v[102:105]
	v_mfma_f32_16x16x32_bf16 v[98:101], v[160:163], v[200:203], v[98:101]
	v_mfma_f32_16x16x32_bf16 v[86:89], v[144:147], v[208:211], v[86:89]
	v_mfma_f32_16x16x32_bf16 v[82:85], v[160:163], v[208:211], v[82:85]
	v_mfma_f32_16x16x32_bf16 v[110:113], v[164:167], v[180:183], v[110:113]
	v_mfma_f32_16x16x32_bf16 v[106:109], v[172:175], v[180:183], v[106:109]
	v_mfma_f32_16x16x32_bf16 v[94:97], v[164:167], v[188:191], v[94:97]
	v_mfma_f32_16x16x32_bf16 v[90:93], v[172:175], v[188:191], v[90:93]
	v_mfma_f32_16x16x32_bf16 v[78:81], v[164:167], v[196:199], v[78:81]
	v_mfma_f32_16x16x32_bf16 v[74:77], v[172:175], v[196:199], v[74:77]
	v_mfma_f32_16x16x32_bf16 v[70:73], v[164:167], v[204:207], v[70:73]
	v_mfma_f32_16x16x32_bf16 v[66:69], v[172:175], v[204:207], v[66:69]
	v_mfma_f32_16x16x32_bf16 v[110:113], v[168:171], v[184:187], v[110:113]
	v_mfma_f32_16x16x32_bf16 v[106:109], v[176:179], v[184:187], v[106:109]
	v_mfma_f32_16x16x32_bf16 v[94:97], v[168:171], v[192:195], v[94:97]
	v_mfma_f32_16x16x32_bf16 v[90:93], v[176:179], v[192:195], v[90:93]
	v_mfma_f32_16x16x32_bf16 v[78:81], v[168:171], v[200:203], v[78:81]
	v_mfma_f32_16x16x32_bf16 v[74:77], v[176:179], v[200:203], v[74:77]
	v_mfma_f32_16x16x32_bf16 v[70:73], v[168:171], v[208:211], v[70:73]
	s_setprio 0
	v_mfma_f32_16x16x32_bf16 v[66:69], v[176:179], v[208:211], v[66:69]
	s_barrier
	s_mov_b32 m0, s53
	v_lshl_add_u64 v[148:149], v[148:149], 0, s[70:71]
	ds_read_b128 v[180:183], v139 offset:49152
	ds_read_b128 v[184:187], v139 offset:50176
	ds_read_b128 v[188:191], v139 offset:51200
	ds_read_b128 v[192:195], v139 offset:52224
	ds_read_b128 v[196:199], v139 offset:53248
	ds_read_b128 v[200:203], v139 offset:54272
	ds_read_b128 v[204:207], v139 offset:55296
	ds_read_b128 v[208:211], v139 offset:56320
	global_load_lds_dwordx4 v[148:149], off
	s_mov_b32 m0, s9
	v_lshl_add_u64 v[148:149], v[150:151], 0, s[70:71]
	global_load_lds_dwordx4 v[148:149], off
	s_mov_b32 m0, s96
	v_lshl_add_u64 v[148:149], s[38:39], 0, v[0:1]
	global_load_lds_dwordx4 v[148:149], off
	s_mov_b32 m0, s92
	v_lshl_add_u64 v[148:149], s[38:39], 0, v[130:131]
	global_load_lds_dwordx4 v[148:149], off
	s_mov_b32 m0, s46
	v_lshl_add_u64 v[148:149], v[212:213], 0, s[70:71]
	global_load_lds_dwordx4 v[148:149], off
	s_mov_b32 m0, s47
	v_lshl_add_u64 v[148:149], v[214:215], 0, s[70:71]
	global_load_lds_dwordx4 v[148:149], off
	s_waitcnt vmcnt(8) lgkmcnt(0)
	s_setprio 1
	s_barrier
	v_mfma_f32_16x16x32_bf16 v[62:65], v[140:143], v[180:183], v[62:65]
	v_mfma_f32_16x16x32_bf16 v[58:61], v[156:159], v[180:183], v[58:61]
	v_mfma_f32_16x16x32_bf16 v[54:57], v[140:143], v[188:191], v[54:57]
	v_mfma_f32_16x16x32_bf16 v[50:53], v[156:159], v[188:191], v[50:53]
	v_mfma_f32_16x16x32_bf16 v[38:41], v[140:143], v[196:199], v[38:41]
	v_mfma_f32_16x16x32_bf16 v[34:37], v[156:159], v[196:199], v[34:37]
	v_mfma_f32_16x16x32_bf16 v[22:25], v[140:143], v[204:207], v[22:25]
	v_mfma_f32_16x16x32_bf16 v[18:21], v[156:159], v[204:207], v[18:21]
	v_mfma_f32_16x16x32_bf16 v[62:65], v[144:147], v[184:187], v[62:65]
	v_mfma_f32_16x16x32_bf16 v[58:61], v[160:163], v[184:187], v[58:61]
	v_mfma_f32_16x16x32_bf16 v[54:57], v[144:147], v[192:195], v[54:57]
	v_mfma_f32_16x16x32_bf16 v[50:53], v[160:163], v[192:195], v[50:53]
	v_mfma_f32_16x16x32_bf16 v[38:41], v[144:147], v[200:203], v[38:41]
	v_mfma_f32_16x16x32_bf16 v[34:37], v[160:163], v[200:203], v[34:37]
	v_mfma_f32_16x16x32_bf16 v[22:25], v[144:147], v[208:211], v[22:25]
	v_mfma_f32_16x16x32_bf16 v[18:21], v[160:163], v[208:211], v[18:21]
	v_mfma_f32_16x16x32_bf16 v[46:49], v[164:167], v[180:183], v[46:49]
	v_mfma_f32_16x16x32_bf16 v[42:45], v[172:175], v[180:183], v[42:45]
	v_mfma_f32_16x16x32_bf16 v[30:33], v[164:167], v[188:191], v[30:33]
	v_mfma_f32_16x16x32_bf16 v[26:29], v[172:175], v[188:191], v[26:29]
	v_mfma_f32_16x16x32_bf16 v[14:17], v[164:167], v[196:199], v[14:17]
	v_mfma_f32_16x16x32_bf16 v[10:13], v[172:175], v[196:199], v[10:13]
	v_mfma_f32_16x16x32_bf16 v[6:9], v[164:167], v[204:207], v[6:9]
	v_mfma_f32_16x16x32_bf16 v[2:5], v[172:175], v[204:207], v[2:5]
	v_mfma_f32_16x16x32_bf16 v[46:49], v[168:171], v[184:187], v[46:49]
	v_mfma_f32_16x16x32_bf16 v[42:45], v[176:179], v[184:187], v[42:45]
	v_mfma_f32_16x16x32_bf16 v[30:33], v[168:171], v[192:195], v[30:33]
	v_mfma_f32_16x16x32_bf16 v[26:29], v[176:179], v[192:195], v[26:29]
	v_mfma_f32_16x16x32_bf16 v[14:17], v[168:171], v[200:203], v[14:17]
	v_mfma_f32_16x16x32_bf16 v[10:13], v[176:179], v[200:203], v[10:13]
	v_mfma_f32_16x16x32_bf16 v[6:9], v[168:171], v[208:211], v[6:9]
	s_setprio 0
	v_mfma_f32_16x16x32_bf16 v[2:5], v[176:179], v[208:211], v[2:5]
	s_barrier
	s_movk_i32 s9, 0x100
	s_andn2_b64 vcc, exec, s[4:5]
	s_mov_b64 s[38:39], -1
	s_mov_b64 s[4:5], 0
	s_cbranch_vccz .LBB0_376
	s_and_b64 vcc, exec, s[14:15]
	s_cbranch_vccz .LBB0_379
	s_barrier

.LBB0_393:
	s_ashr_i32 s19, s18, 31
	s_lshl_b64 s[24:25], s[18:19], 16
	s_add_u32 s24, s29, s24
	s_addc_u32 s25, s38, s25
	s_and_b64 s[4:5], s[4:5], exec
	s_cselect_b32 s5, s25, s27
	s_cselect_b32 s4, s24, s26
	s_add_i32 s19, 0, 0x10000
	s_add_i32 s48, 0, 0x14000
	v_add_u32_e32 v14, s19, v137
	v_add_u32_e32 v30, s48, v137
	.p2align 6
	ds_read_b128 v[2:5], v14
	ds_read_b128 v[6:9], v14 offset:1024
	ds_read_b128 v[10:13], v14 offset:2048
	ds_read_b128 v[14:17], v14 offset:3072
	ds_read_b128 v[18:21], v30
	ds_read_b128 v[22:25], v30 offset:1024
	ds_read_b128 v[26:29], v30 offset:2048
	ds_read_b128 v[30:33], v30 offset:3072
	s_add_u32 s26, s36, 0x58080
	s_addc_u32 s27, s37, 0
	v_lshl_add_u64 v[66:67], s[26:27], 0, v[134:135]
	s_add_i32 m0, s40, 0xc000
	ds_read_b128 v[34:37], v139
	ds_read_b128 v[38:41], v139 offset:1024
	ds_read_b128 v[42:45], v139 offset:2048
	ds_read_b128 v[46:49], v139 offset:3072
	ds_read_b128 v[50:53], v139 offset:4096
	ds_read_b128 v[54:57], v139 offset:5120
	ds_read_b128 v[58:61], v139 offset:6144
	ds_read_b128 v[62:65], v139 offset:7168
	global_load_lds_dwordx4 v[66:67], off
	s_add_i32 m0, s40, 0xe000
	v_lshl_add_u64 v[66:67], s[26:27], 0, v[132:133]
	global_load_lds_dwordx4 v[66:67], off
	s_waitcnt vmcnt(8) lgkmcnt(0)
	s_setprio 1
	s_barrier
	v_mfma_f32_16x16x32_bf16 v[66:69], v[2:5], v[34:37], 0
	v_mfma_f32_16x16x32_bf16 v[70:73], v[10:13], v[34:37], 0
	v_mfma_f32_16x16x32_bf16 v[74:77], v[2:5], v[42:45], 0
	v_mfma_f32_16x16x32_bf16 v[78:81], v[10:13], v[42:45], 0
	v_mfma_f32_16x16x32_bf16 v[82:85], v[2:5], v[50:53], 0
	v_mfma_f32_16x16x32_bf16 v[86:89], v[10:13], v[50:53], 0
	v_mfma_f32_16x16x32_bf16 v[90:93], v[2:5], v[58:61], 0
	v_mfma_f32_16x16x32_bf16 v[94:97], v[10:13], v[58:61], 0
	v_mfma_f32_16x16x32_bf16 v[66:69], v[6:9], v[38:41], v[66:69]
	v_mfma_f32_16x16x32_bf16 v[70:73], v[14:17], v[38:41], v[70:73]
	v_mfma_f32_16x16x32_bf16 v[74:77], v[6:9], v[46:49], v[74:77]
	v_mfma_f32_16x16x32_bf16 v[78:81], v[14:17], v[46:49], v[78:81]
	v_mfma_f32_16x16x32_bf16 v[82:85], v[6:9], v[54:57], v[82:85]
	v_mfma_f32_16x16x32_bf16 v[86:89], v[14:17], v[54:57], v[86:89]
	v_mfma_f32_16x16x32_bf16 v[90:93], v[6:9], v[62:65], v[90:93]
	v_mfma_f32_16x16x32_bf16 v[94:97], v[14:17], v[62:65], v[94:97]
	v_mfma_f32_16x16x32_bf16 v[98:101], v[18:21], v[34:37], 0
	v_mfma_f32_16x16x32_bf16 v[34:37], v[26:29], v[34:37], 0
	v_mfma_f32_16x16x32_bf16 v[98:101], v[22:25], v[38:41], v[98:101]
	v_mfma_f32_16x16x32_bf16 v[34:37], v[30:33], v[38:41], v[34:37]
	v_mfma_f32_16x16x32_bf16 v[38:41], v[18:21], v[42:45], 0
	v_mfma_f32_16x16x32_bf16 v[42:45], v[26:29], v[42:45], 0
	v_mfma_f32_16x16x32_bf16 v[102:105], v[30:33], v[46:49], v[42:45]
	v_mfma_f32_16x16x32_bf16 v[42:45], v[18:21], v[50:53], 0
	v_mfma_f32_16x16x32_bf16 v[114:117], v[22:25], v[54:57], v[42:45]
	v_mfma_f32_16x16x32_bf16 v[42:45], v[26:29], v[50:53], 0
	v_mfma_f32_16x16x32_bf16 v[50:53], v[30:33], v[54:57], v[42:45]
	v_mfma_f32_16x16x32_bf16 v[42:45], v[18:21], v[58:61], 0
	v_mfma_f32_16x16x32_bf16 v[54:57], v[22:25], v[62:65], v[42:45]
	v_mfma_f32_16x16x32_bf16 v[42:45], v[26:29], v[58:61], 0
	v_mfma_f32_16x16x32_bf16 v[38:41], v[22:25], v[46:49], v[38:41]
	s_setprio 0
	v_mfma_f32_16x16x32_bf16 v[58:61], v[30:33], v[62:65], v[42:45]
	s_barrier
	s_add_i32 s19, s19, s39
	v_lshl_add_u64 v[148:149], s[4:5], 0, v[0:1]
	s_mov_b32 m0, s19
	s_nop 0
	ds_read_b128 v[42:45], v139 offset:16384
	ds_read_b128 v[46:49], v139 offset:17408
	ds_read_b128 v[62:65], v139 offset:18432
	ds_read_b128 v[106:109], v139 offset:19456
	ds_read_b128 v[110:113], v139 offset:20480
	ds_read_b128 v[118:121], v139 offset:21504
	ds_read_b128 v[122:125], v139 offset:22528
	ds_read_b128 v[126:129], v139 offset:23552
	global_load_lds_dwordx4 v[148:149], off
	s_add_i32 m0, s19, 0x2000
	s_add_u32 s26, s4, 0x8000
	v_lshl_add_u64 v[150:151], s[4:5], 0, v[130:131]
	s_addc_u32 s27, s5, 0
	s_add_i32 s19, s48, s39
	global_load_lds_dwordx4 v[150:151], off
	v_lshl_add_u64 v[140:141], s[26:27], 0, v[0:1]
	s_mov_b32 m0, s19
	v_lshl_add_u64 v[252:253], s[22:23], 0, v[134:135]
	global_load_lds_dwordx4 v[140:141], off
	v_lshl_add_u64 v[140:141], s[26:27], 0, v[130:131]
	s_add_i32 m0, s19, 0x2000
	v_lshl_add_u64 v[242:243], s[22:23], 0, v[132:133]
	global_load_lds_dwordx4 v[140:141], off
	s_mov_b32 m0, s40
	s_nop 0
	global_load_lds_dwordx4 v[252:253], off
	s_mov_b32 m0, s41
	s_nop 0
	global_load_lds_dwordx4 v[242:243], off
	s_waitcnt vmcnt(8) lgkmcnt(0)
	s_setprio 1
	s_barrier
	v_mfma_f32_16x16x32_bf16 v[140:143], v[2:5], v[42:45], 0
	v_mfma_f32_16x16x32_bf16 v[156:159], v[2:5], v[62:65], 0
	v_mfma_f32_16x16x32_bf16 v[164:167], v[2:5], v[110:113], 0
	v_mfma_f32_16x16x32_bf16 v[2:5], v[2:5], v[122:125], 0
	v_mfma_f32_16x16x32_bf16 v[140:143], v[6:9], v[46:49], v[140:143]
	v_mfma_f32_16x16x32_bf16 v[156:159], v[6:9], v[106:109], v[156:159]
	v_mfma_f32_16x16x32_bf16 v[164:167], v[6:9], v[118:121], v[164:167]
	v_mfma_f32_16x16x32_bf16 v[2:5], v[6:9], v[126:129], v[2:5]
	v_mfma_f32_16x16x32_bf16 v[6:9], v[10:13], v[122:125], 0
	v_mfma_f32_16x16x32_bf16 v[144:147], v[10:13], v[42:45], 0
	v_mfma_f32_16x16x32_bf16 v[160:163], v[10:13], v[62:65], 0
	v_mfma_f32_16x16x32_bf16 v[168:171], v[10:13], v[110:113], 0
	v_mfma_f32_16x16x32_bf16 v[6:9], v[14:17], v[126:129], v[6:9]
	v_mfma_f32_16x16x32_bf16 v[144:147], v[14:17], v[46:49], v[144:147]
	v_mfma_f32_16x16x32_bf16 v[160:163], v[14:17], v[106:109], v[160:163]
	v_mfma_f32_16x16x32_bf16 v[168:171], v[14:17], v[118:121], v[168:171]
	v_mfma_f32_16x16x32_bf16 v[10:13], v[18:21], v[42:45], 0
	v_mfma_f32_16x16x32_bf16 v[172:175], v[22:25], v[46:49], v[10:13]
	v_mfma_f32_16x16x32_bf16 v[10:13], v[26:29], v[42:45], 0
	v_mfma_f32_16x16x32_bf16 v[176:179], v[30:33], v[46:49], v[10:13]
	v_mfma_f32_16x16x32_bf16 v[10:13], v[18:21], v[62:65], 0
	v_mfma_f32_16x16x32_bf16 v[180:183], v[22:25], v[106:109], v[10:13]
	v_mfma_f32_16x16x32_bf16 v[10:13], v[26:29], v[62:65], 0
	v_mfma_f32_16x16x32_bf16 v[184:187], v[30:33], v[106:109], v[10:13]
	v_mfma_f32_16x16x32_bf16 v[10:13], v[18:21], v[110:113], 0
	v_mfma_f32_16x16x32_bf16 v[188:191], v[22:25], v[118:121], v[10:13]
	v_mfma_f32_16x16x32_bf16 v[10:13], v[26:29], v[110:113], 0
	v_mfma_f32_16x16x32_bf16 v[192:195], v[30:33], v[118:121], v[10:13]
	v_mfma_f32_16x16x32_bf16 v[10:13], v[18:21], v[122:125], 0
	v_mfma_f32_16x16x32_bf16 v[18:21], v[22:25], v[126:129], v[10:13]
	v_mfma_f32_16x16x32_bf16 v[10:13], v[26:29], v[122:125], 0
	s_setprio 0
	v_mfma_f32_16x16x32_bf16 v[22:25], v[30:33], v[126:129], v[10:13]
	s_barrier
	s_add_i32 s19, 0, 0x18000
	s_nop 3
	v_add_u32_e32 v10, s19, v137
	s_add_i32 s36, 0, 0x1c000
	ds_read_b128 v[118:121], v10
	ds_read_b128 v[196:199], v10 offset:1024
	ds_read_b128 v[200:203], v10 offset:2048
	ds_read_b128 v[204:207], v10 offset:3072
	v_add_u32_e32 v10, s36, v137
	ds_read_b128 v[208:211], v10
	ds_read_b128 v[212:215], v10 offset:1024
	ds_read_b128 v[216:219], v10 offset:2048
	ds_read_b128 v[220:223], v10 offset:3072
	s_add_u32 s26, s22, 0x58000
	s_addc_u32 s27, s23, 0
	s_mov_b32 m0, s42
	v_lshl_add_u64 v[10:11], s[26:27], 0, v[134:135]
	ds_read_b128 v[26:29], v139 offset:32768
	ds_read_b128 v[30:33], v139 offset:33792
	ds_read_b128 v[62:65], v139 offset:34816
	ds_read_b128 v[224:227], v139 offset:35840
	ds_read_b128 v[228:231], v139 offset:36864
	ds_read_b128 v[232:235], v139 offset:37888
	ds_read_b128 v[236:239], v139 offset:38912
	ds_read_b128 v[248:251], v139 offset:39936
	global_load_lds_dwordx4 v[10:11], off
	s_mov_b32 m0, s43
	v_lshl_add_u64 v[10:11], s[26:27], 0, v[132:133]
	global_load_lds_dwordx4 v[10:11], off
	s_waitcnt vmcnt(8) lgkmcnt(0)
	s_setprio 1
	s_barrier
	v_mfma_f32_16x16x32_bf16 v[10:13], v[118:121], v[26:29], v[66:69]
	v_mfma_f32_16x16x32_bf16 v[106:109], v[196:199], v[30:33], v[10:13]
	v_mfma_f32_16x16x32_bf16 v[10:13], v[200:203], v[26:29], v[70:73]
	v_mfma_f32_16x16x32_bf16 v[110:113], v[204:207], v[30:33], v[10:13]
	v_mfma_f32_16x16x32_bf16 v[10:13], v[118:121], v[62:65], v[74:77]
	v_mfma_f32_16x16x32_bf16 v[74:77], v[196:199], v[224:227], v[10:13]
	v_mfma_f32_16x16x32_bf16 v[10:13], v[200:203], v[62:65], v[78:81]
	v_mfma_f32_16x16x32_bf16 v[78:81], v[204:207], v[224:227], v[10:13]
	v_mfma_f32_16x16x32_bf16 v[10:13], v[118:121], v[228:231], v[82:85]
	v_mfma_f32_16x16x32_bf16 v[42:45], v[196:199], v[232:235], v[10:13]
	v_mfma_f32_16x16x32_bf16 v[10:13], v[200:203], v[228:231], v[86:89]
	v_mfma_f32_16x16x32_bf16 v[46:49], v[204:207], v[232:235], v[10:13]
	v_mfma_f32_16x16x32_bf16 v[10:13], v[118:121], v[236:239], v[90:93]
	v_mfma_f32_16x16x32_bf16 v[14:17], v[200:203], v[236:239], v[94:97]
	v_mfma_f32_16x16x32_bf16 v[10:13], v[196:199], v[248:251], v[10:13]
	v_mfma_f32_16x16x32_bf16 v[14:17], v[204:207], v[248:251], v[14:17]
	v_mfma_f32_16x16x32_bf16 v[66:69], v[208:211], v[26:29], v[98:101]
	v_mfma_f32_16x16x32_bf16 v[26:29], v[216:219], v[26:29], v[34:37]
	v_mfma_f32_16x16x32_bf16 v[126:129], v[220:223], v[30:33], v[26:29]
	v_mfma_f32_16x16x32_bf16 v[26:29], v[208:211], v[62:65], v[38:41]
	v_mfma_f32_16x16x32_bf16 v[98:101], v[212:215], v[224:227], v[26:29]
	v_mfma_f32_16x16x32_bf16 v[26:29], v[216:219], v[62:65], v[102:105]
	v_mfma_f32_16x16x32_bf16 v[102:105], v[220:223], v[224:227], v[26:29]
	v_mfma_f32_16x16x32_bf16 v[26:29], v[208:211], v[228:231], v[114:117]
	v_mfma_f32_16x16x32_bf16 v[122:125], v[212:215], v[30:33], v[66:69]
	v_mfma_f32_16x16x32_bf16 v[66:69], v[212:215], v[232:235], v[26:29]
	v_mfma_f32_16x16x32_bf16 v[26:29], v[216:219], v[228:231], v[50:53]
	v_mfma_f32_16x16x32_bf16 v[70:73], v[220:223], v[232:235], v[26:29]
	v_mfma_f32_16x16x32_bf16 v[26:29], v[208:211], v[236:239], v[54:57]
	v_mfma_f32_16x16x32_bf16 v[34:37], v[212:215], v[248:251], v[26:29]
	v_mfma_f32_16x16x32_bf16 v[26:29], v[216:219], v[236:239], v[58:61]
	s_setprio 0
	v_mfma_f32_16x16x32_bf16 v[38:41], v[220:223], v[248:251], v[26:29]
	s_barrier
	s_add_i32 s19, s19, s39
	s_nop 3
	v_lshl_add_u64 v[26:27], v[148:149], 0, s[70:71]
	s_mov_b32 m0, s19
	ds_read_b128 v[50:53], v139 offset:49152
	ds_read_b128 v[54:57], v139 offset:50176
	ds_read_b128 v[86:89], v139 offset:51200
	ds_read_b128 v[224:227], v139 offset:52224
	ds_read_b128 v[228:231], v139 offset:53248
	ds_read_b128 v[232:235], v139 offset:54272
	ds_read_b128 v[236:239], v139 offset:55296
	ds_read_b128 v[248:251], v139 offset:56320
	global_load_lds_dwordx4 v[26:27], off
	s_add_i32 m0, s19, 0x2000
	s_add_u32 s4, s4, 0x8080
	v_lshl_add_u64 v[26:27], v[150:151], 0, s[70:71]
	s_addc_u32 s5, s5, 0
	s_add_i32 s19, s36, s39
	global_load_lds_dwordx4 v[26:27], off
	s_mov_b32 m0, s19
	v_lshl_add_u64 v[26:27], s[4:5], 0, v[0:1]
	global_load_lds_dwordx4 v[26:27], off
	s_add_i32 m0, s19, 0x2000
	v_lshl_add_u64 v[26:27], s[4:5], 0, v[130:131]
	global_load_lds_dwordx4 v[26:27], off
	s_mov_b32 m0, s44
	v_lshl_add_u64 v[26:27], v[252:253], 0, s[70:71]
	global_load_lds_dwordx4 v[26:27], off
	s_mov_b32 m0, s45
	v_lshl_add_u64 v[26:27], v[242:243], 0, s[70:71]
	global_load_lds_dwordx4 v[26:27], off
	s_waitcnt vmcnt(8) lgkmcnt(0)
	s_setprio 1
	s_barrier
	v_mfma_f32_16x16x32_bf16 v[26:29], v[118:121], v[50:53], v[140:143]
	v_mfma_f32_16x16x32_bf16 v[90:93], v[196:199], v[54:57], v[26:29]
	v_mfma_f32_16x16x32_bf16 v[26:29], v[200:203], v[50:53], v[144:147]
	v_mfma_f32_16x16x32_bf16 v[94:97], v[204:207], v[54:57], v[26:29]
	v_mfma_f32_16x16x32_bf16 v[26:29], v[118:121], v[86:89], v[156:159]
	v_mfma_f32_16x16x32_bf16 v[58:61], v[196:199], v[224:227], v[26:29]
	v_mfma_f32_16x16x32_bf16 v[26:29], v[200:203], v[86:89], v[160:163]
	v_mfma_f32_16x16x32_bf16 v[62:65], v[204:207], v[224:227], v[26:29]
	v_mfma_f32_16x16x32_bf16 v[26:29], v[118:121], v[228:231], v[164:167]
	v_mfma_f32_16x16x32_bf16 v[30:33], v[200:203], v[228:231], v[168:171]
	v_mfma_f32_16x16x32_bf16 v[2:5], v[118:121], v[236:239], v[2:5]
	v_mfma_f32_16x16x32_bf16 v[6:9], v[200:203], v[236:239], v[6:9]
	v_mfma_f32_16x16x32_bf16 v[26:29], v[196:199], v[232:235], v[26:29]
	v_mfma_f32_16x16x32_bf16 v[30:33], v[204:207], v[232:235], v[30:33]
	v_mfma_f32_16x16x32_bf16 v[2:5], v[196:199], v[248:251], v[2:5]
	v_mfma_f32_16x16x32_bf16 v[6:9], v[204:207], v[248:251], v[6:9]
	v_mfma_f32_16x16x32_bf16 v[82:85], v[208:211], v[50:53], v[172:175]
	v_mfma_f32_16x16x32_bf16 v[50:53], v[216:219], v[50:53], v[176:179]
	v_mfma_f32_16x16x32_bf16 v[118:121], v[220:223], v[54:57], v[50:53]
	v_mfma_f32_16x16x32_bf16 v[50:53], v[208:211], v[86:89], v[180:183]
	v_mfma_f32_16x16x32_bf16 v[114:117], v[212:215], v[54:57], v[82:85]
	v_mfma_f32_16x16x32_bf16 v[82:85], v[212:215], v[224:227], v[50:53]
	v_mfma_f32_16x16x32_bf16 v[50:53], v[216:219], v[86:89], v[184:187]
	v_mfma_f32_16x16x32_bf16 v[86:89], v[220:223], v[224:227], v[50:53]
	v_mfma_f32_16x16x32_bf16 v[50:53], v[208:211], v[228:231], v[188:191]
	v_mfma_f32_16x16x32_bf16 v[54:57], v[216:219], v[228:231], v[192:195]
	v_mfma_f32_16x16x32_bf16 v[18:21], v[208:211], v[236:239], v[18:21]
	v_mfma_f32_16x16x32_bf16 v[22:25], v[216:219], v[236:239], v[22:25]
	v_mfma_f32_16x16x32_bf16 v[50:53], v[212:215], v[232:235], v[50:53]
	v_mfma_f32_16x16x32_bf16 v[54:57], v[220:223], v[232:235], v[54:57]
	v_mfma_f32_16x16x32_bf16 v[18:21], v[212:215], v[248:251], v[18:21]
	s_setprio 0
	v_mfma_f32_16x16x32_bf16 v[22:25], v[220:223], v[248:251], v[22:25]
	s_barrier
	s_andn2_b64 vcc, exec, s[14:15]
	s_cbranch_vccnz .LBB0_395
	s_barrier

.LBB0_701:
	s_add_i32 s75, s26, 2
	s_add_u32 s9, s60, 0xfffc0080
	s_addc_u32 s27, s61, -1
	s_add_i32 s78, 0, 0x10000
	s_cmp_eq_u32 s19, s26
	s_cselect_b32 s73, s23, s27
	s_cselect_b32 s72, s22, s9
	s_cselect_b32 s27, s25, s29
	s_cselect_b32 s26, s24, s28
	s_add_i32 s9, 0, 0x14000
	s_waitcnt vmcnt(0)
	v_add_u32_e32 v142, s78, v177
	v_add_u32_e32 v148, s9, v177
	ds_read_b128 v[130:133], v142
	ds_read_b128 v[134:137], v142 offset:1024
	ds_read_b128 v[138:141], v142 offset:2048
	ds_read_b128 v[142:145], v142 offset:3072
	ds_read_b128 v[164:167], v148
	ds_read_b128 v[168:171], v148 offset:1024
	ds_read_b128 v[172:175], v148 offset:2048
	ds_read_b128 v[180:183], v148 offset:3072
	v_lshl_add_u64 v[148:149], s[60:61], 0, v[160:161]
	s_add_i32 m0, s37, 0xc000
	ds_read_b128 v[184:187], v179
	ds_read_b128 v[188:191], v179 offset:1024
	ds_read_b128 v[192:195], v179 offset:2048
	ds_read_b128 v[196:199], v179 offset:3072
	ds_read_b128 v[200:203], v179 offset:4096
	ds_read_b128 v[204:207], v179 offset:5120
	ds_read_b128 v[208:211], v179 offset:6144
	ds_read_b128 v[212:215], v179 offset:7168
	global_load_lds_dwordx4 v[148:149], off
	s_add_i32 m0, s37, 0xe000
	v_lshl_add_u64 v[148:149], s[60:61], 0, v[162:163]
	global_load_lds_dwordx4 v[148:149], off
	s_waitcnt vmcnt(8) lgkmcnt(0)
	s_setprio 1
	s_barrier
	v_mfma_f32_16x16x32_bf16 v[126:129], v[130:133], v[184:187], v[126:129]
	v_mfma_f32_16x16x32_bf16 v[122:125], v[138:141], v[184:187], v[122:125]
	v_mfma_f32_16x16x32_bf16 v[110:113], v[130:133], v[192:195], v[110:113]
	v_mfma_f32_16x16x32_bf16 v[106:109], v[138:141], v[192:195], v[106:109]
	v_mfma_f32_16x16x32_bf16 v[94:97], v[130:133], v[200:203], v[94:97]
	v_mfma_f32_16x16x32_bf16 v[90:93], v[138:141], v[200:203], v[90:93]
	v_mfma_f32_16x16x32_bf16 v[78:81], v[130:133], v[208:211], v[78:81]
	v_mfma_f32_16x16x32_bf16 v[74:77], v[138:141], v[208:211], v[74:77]
	v_mfma_f32_16x16x32_bf16 v[126:129], v[134:137], v[188:191], v[126:129]
	v_mfma_f32_16x16x32_bf16 v[122:125], v[142:145], v[188:191], v[122:125]
	v_mfma_f32_16x16x32_bf16 v[110:113], v[134:137], v[196:199], v[110:113]
	v_mfma_f32_16x16x32_bf16 v[106:109], v[142:145], v[196:199], v[106:109]
	v_mfma_f32_16x16x32_bf16 v[94:97], v[134:137], v[204:207], v[94:97]
	v_mfma_f32_16x16x32_bf16 v[90:93], v[142:145], v[204:207], v[90:93]
	v_mfma_f32_16x16x32_bf16 v[78:81], v[134:137], v[212:215], v[78:81]
	v_mfma_f32_16x16x32_bf16 v[74:77], v[142:145], v[212:215], v[74:77]
	v_mfma_f32_16x16x32_bf16 v[118:121], v[164:167], v[184:187], v[118:121]
	v_mfma_f32_16x16x32_bf16 v[114:117], v[172:175], v[184:187], v[114:117]
	v_mfma_f32_16x16x32_bf16 v[102:105], v[164:167], v[192:195], v[102:105]
	v_mfma_f32_16x16x32_bf16 v[98:101], v[172:175], v[192:195], v[98:101]
	v_mfma_f32_16x16x32_bf16 v[86:89], v[164:167], v[200:203], v[86:89]
	v_mfma_f32_16x16x32_bf16 v[82:85], v[172:175], v[200:203], v[82:85]
	v_mfma_f32_16x16x32_bf16 v[70:73], v[164:167], v[208:211], v[70:73]
	v_mfma_f32_16x16x32_bf16 v[66:69], v[172:175], v[208:211], v[66:69]
	v_mfma_f32_16x16x32_bf16 v[118:121], v[168:171], v[188:191], v[118:121]
	v_mfma_f32_16x16x32_bf16 v[114:117], v[180:183], v[188:191], v[114:117]
	v_mfma_f32_16x16x32_bf16 v[102:105], v[168:171], v[196:199], v[102:105]
	v_mfma_f32_16x16x32_bf16 v[98:101], v[180:183], v[196:199], v[98:101]
	v_mfma_f32_16x16x32_bf16 v[86:89], v[168:171], v[204:207], v[86:89]
	v_mfma_f32_16x16x32_bf16 v[82:85], v[180:183], v[204:207], v[82:85]
	v_mfma_f32_16x16x32_bf16 v[70:73], v[168:171], v[212:215], v[70:73]
	s_setprio 0
	v_mfma_f32_16x16x32_bf16 v[66:69], v[180:183], v[212:215], v[66:69]
	s_barrier
	s_add_i32 s78, s78, s41
	v_lshl_add_u64 v[148:149], s[26:27], 0, v[0:1]
	s_mov_b32 m0, s78
	ds_read_b128 v[184:187], v179 offset:16384
	ds_read_b128 v[188:191], v179 offset:17408
	ds_read_b128 v[192:195], v179 offset:18432
	ds_read_b128 v[196:199], v179 offset:19456
	ds_read_b128 v[200:203], v179 offset:20480
	ds_read_b128 v[204:207], v179 offset:21504
	ds_read_b128 v[208:211], v179 offset:22528
	ds_read_b128 v[212:215], v179 offset:23552
	global_load_lds_dwordx4 v[148:149], off
	s_add_i32 m0, s78, 0x2000
	s_add_u32 s78, s26, 0x40000
	v_lshl_add_u64 v[150:151], s[26:27], 0, v[158:159]
	s_addc_u32 s79, s27, 0
	s_add_i32 s9, s9, s41
	global_load_lds_dwordx4 v[150:151], off
	v_lshl_add_u64 v[216:217], s[78:79], 0, v[0:1]
	s_mov_b32 m0, s9
	v_lshl_add_u64 v[218:219], s[72:73], 0, v[156:157]
	global_load_lds_dwordx4 v[216:217], off
	s_add_i32 m0, s9, 0x2000
	v_lshl_add_u64 v[216:217], s[78:79], 0, v[158:159]
	global_load_lds_dwordx4 v[216:217], off
	s_mov_b32 m0, s37
	v_lshl_add_u64 v[216:217], s[72:73], 0, v[146:147]
	global_load_lds_dwordx4 v[216:217], off
	s_mov_b32 m0, s39
	s_nop 0
	global_load_lds_dwordx4 v[218:219], off
	s_waitcnt vmcnt(8) lgkmcnt(0)
	s_setprio 1
	s_barrier
	v_mfma_f32_16x16x32_bf16 v[62:65], v[130:133], v[184:187], v[62:65]
	v_mfma_f32_16x16x32_bf16 v[58:61], v[138:141], v[184:187], v[58:61]
	v_mfma_f32_16x16x32_bf16 v[46:49], v[130:133], v[192:195], v[46:49]
	v_mfma_f32_16x16x32_bf16 v[42:45], v[138:141], v[192:195], v[42:45]
	v_mfma_f32_16x16x32_bf16 v[30:33], v[130:133], v[200:203], v[30:33]
	v_mfma_f32_16x16x32_bf16 v[26:29], v[138:141], v[200:203], v[26:29]
	v_mfma_f32_16x16x32_bf16 v[14:17], v[130:133], v[208:211], v[14:17]
	v_mfma_f32_16x16x32_bf16 v[10:13], v[138:141], v[208:211], v[10:13]
	v_mfma_f32_16x16x32_bf16 v[62:65], v[134:137], v[188:191], v[62:65]
	v_mfma_f32_16x16x32_bf16 v[58:61], v[142:145], v[188:191], v[58:61]
	v_mfma_f32_16x16x32_bf16 v[46:49], v[134:137], v[196:199], v[46:49]
	v_mfma_f32_16x16x32_bf16 v[42:45], v[142:145], v[196:199], v[42:45]
	v_mfma_f32_16x16x32_bf16 v[30:33], v[134:137], v[204:207], v[30:33]
	v_mfma_f32_16x16x32_bf16 v[26:29], v[142:145], v[204:207], v[26:29]
	v_mfma_f32_16x16x32_bf16 v[14:17], v[134:137], v[212:215], v[14:17]
	v_mfma_f32_16x16x32_bf16 v[10:13], v[142:145], v[212:215], v[10:13]
	v_mfma_f32_16x16x32_bf16 v[54:57], v[164:167], v[184:187], v[54:57]
	v_mfma_f32_16x16x32_bf16 v[50:53], v[172:175], v[184:187], v[50:53]
	v_mfma_f32_16x16x32_bf16 v[38:41], v[164:167], v[192:195], v[38:41]
	v_mfma_f32_16x16x32_bf16 v[34:37], v[172:175], v[192:195], v[34:37]
	v_mfma_f32_16x16x32_bf16 v[22:25], v[164:167], v[200:203], v[22:25]
	v_mfma_f32_16x16x32_bf16 v[18:21], v[172:175], v[200:203], v[18:21]
	v_mfma_f32_16x16x32_bf16 v[6:9], v[164:167], v[208:211], v[6:9]
	v_mfma_f32_16x16x32_bf16 v[2:5], v[172:175], v[208:211], v[2:5]
	v_mfma_f32_16x16x32_bf16 v[54:57], v[168:171], v[188:191], v[54:57]
	v_mfma_f32_16x16x32_bf16 v[50:53], v[180:183], v[188:191], v[50:53]
	v_mfma_f32_16x16x32_bf16 v[38:41], v[168:171], v[196:199], v[38:41]
	v_mfma_f32_16x16x32_bf16 v[34:37], v[180:183], v[196:199], v[34:37]
	v_mfma_f32_16x16x32_bf16 v[22:25], v[168:171], v[204:207], v[22:25]
	v_mfma_f32_16x16x32_bf16 v[18:21], v[180:183], v[204:207], v[18:21]
	v_mfma_f32_16x16x32_bf16 v[6:9], v[168:171], v[212:215], v[6:9]
	s_setprio 0
	v_mfma_f32_16x16x32_bf16 v[2:5], v[180:183], v[212:215], v[2:5]
	s_barrier
	s_add_i32 s9, 0, 0x18000
	s_add_i32 s78, 0, 0x1c000
	v_add_u32_e32 v142, s9, v177
	v_add_u32_e32 v180, s78, v177
	ds_read_b128 v[130:133], v142
	ds_read_b128 v[134:137], v142 offset:1024
	ds_read_b128 v[138:141], v142 offset:2048
	ds_read_b128 v[142:145], v142 offset:3072
	ds_read_b128 v[164:167], v180
	ds_read_b128 v[168:171], v180 offset:1024
	ds_read_b128 v[172:175], v180 offset:2048
	ds_read_b128 v[180:183], v180 offset:3072
	s_add_u32 s72, s72, 0x40000
	s_addc_u32 s73, s73, 0
	s_mov_b32 m0, s44
	v_lshl_add_u64 v[220:221], s[72:73], 0, v[146:147]
	ds_read_b128 v[184:187], v179 offset:32768
	ds_read_b128 v[188:191], v179 offset:33792
	ds_read_b128 v[192:195], v179 offset:34816
	ds_read_b128 v[196:199], v179 offset:35840
	ds_read_b128 v[200:203], v179 offset:36864
	ds_read_b128 v[204:207], v179 offset:37888
	ds_read_b128 v[208:211], v179 offset:38912
	ds_read_b128 v[212:215], v179 offset:39936
	global_load_lds_dwordx4 v[220:221], off
	s_mov_b32 m0, s45
	v_lshl_add_u64 v[220:221], s[72:73], 0, v[156:157]
	global_load_lds_dwordx4 v[220:221], off
	s_waitcnt vmcnt(8) lgkmcnt(0)
	s_setprio 1
	s_barrier
	v_mfma_f32_16x16x32_bf16 v[126:129], v[130:133], v[184:187], v[126:129]
	v_mfma_f32_16x16x32_bf16 v[122:125], v[138:141], v[184:187], v[122:125]
	v_mfma_f32_16x16x32_bf16 v[110:113], v[130:133], v[192:195], v[110:113]
	v_mfma_f32_16x16x32_bf16 v[106:109], v[138:141], v[192:195], v[106:109]
	v_mfma_f32_16x16x32_bf16 v[94:97], v[130:133], v[200:203], v[94:97]
	v_mfma_f32_16x16x32_bf16 v[90:93], v[138:141], v[200:203], v[90:93]
	v_mfma_f32_16x16x32_bf16 v[78:81], v[130:133], v[208:211], v[78:81]
	v_mfma_f32_16x16x32_bf16 v[74:77], v[138:141], v[208:211], v[74:77]
	v_mfma_f32_16x16x32_bf16 v[126:129], v[134:137], v[188:191], v[126:129]
	v_mfma_f32_16x16x32_bf16 v[122:125], v[142:145], v[188:191], v[122:125]
	v_mfma_f32_16x16x32_bf16 v[110:113], v[134:137], v[196:199], v[110:113]
	v_mfma_f32_16x16x32_bf16 v[106:109], v[142:145], v[196:199], v[106:109]
	v_mfma_f32_16x16x32_bf16 v[94:97], v[134:137], v[204:207], v[94:97]
	v_mfma_f32_16x16x32_bf16 v[90:93], v[142:145], v[204:207], v[90:93]
	v_mfma_f32_16x16x32_bf16 v[78:81], v[134:137], v[212:215], v[78:81]
	v_mfma_f32_16x16x32_bf16 v[74:77], v[142:145], v[212:215], v[74:77]
	v_mfma_f32_16x16x32_bf16 v[118:121], v[164:167], v[184:187], v[118:121]
	v_mfma_f32_16x16x32_bf16 v[114:117], v[172:175], v[184:187], v[114:117]
	v_mfma_f32_16x16x32_bf16 v[102:105], v[164:167], v[192:195], v[102:105]
	v_mfma_f32_16x16x32_bf16 v[98:101], v[172:175], v[192:195], v[98:101]
	v_mfma_f32_16x16x32_bf16 v[86:89], v[164:167], v[200:203], v[86:89]
	v_mfma_f32_16x16x32_bf16 v[82:85], v[172:175], v[200:203], v[82:85]
	v_mfma_f32_16x16x32_bf16 v[70:73], v[164:167], v[208:211], v[70:73]
	v_mfma_f32_16x16x32_bf16 v[66:69], v[172:175], v[208:211], v[66:69]
	v_mfma_f32_16x16x32_bf16 v[118:121], v[168:171], v[188:191], v[118:121]
	v_mfma_f32_16x16x32_bf16 v[114:117], v[180:183], v[188:191], v[114:117]
	v_mfma_f32_16x16x32_bf16 v[102:105], v[168:171], v[196:199], v[102:105]
	v_mfma_f32_16x16x32_bf16 v[98:101], v[180:183], v[196:199], v[98:101]
	v_mfma_f32_16x16x32_bf16 v[86:89], v[168:171], v[204:207], v[86:89]
	v_mfma_f32_16x16x32_bf16 v[82:85], v[180:183], v[204:207], v[82:85]
	v_mfma_f32_16x16x32_bf16 v[70:73], v[168:171], v[212:215], v[70:73]
	s_setprio 0
	v_mfma_f32_16x16x32_bf16 v[66:69], v[180:183], v[212:215], v[66:69]
	s_barrier
	s_add_i32 s9, s9, s41
	v_lshl_add_u64 v[148:149], v[148:149], 0, s[70:71]
	s_mov_b32 m0, s9
	ds_read_b128 v[184:187], v179 offset:49152
	ds_read_b128 v[188:191], v179 offset:50176
	ds_read_b128 v[192:195], v179 offset:51200
	ds_read_b128 v[196:199], v179 offset:52224
	ds_read_b128 v[200:203], v179 offset:53248
	ds_read_b128 v[204:207], v179 offset:54272
	ds_read_b128 v[208:211], v179 offset:55296
	ds_read_b128 v[212:215], v179 offset:56320
	global_load_lds_dwordx4 v[148:149], off
	s_add_i32 m0, s9, 0x2000
	s_add_u32 s26, s26, 0x40080
	v_lshl_add_u64 v[148:149], v[150:151], 0, s[70:71]
	s_addc_u32 s27, s27, 0
	s_add_i32 s9, s78, s41
	global_load_lds_dwordx4 v[148:149], off
	s_mov_b32 m0, s9
	v_lshl_add_u64 v[148:149], s[26:27], 0, v[0:1]
	global_load_lds_dwordx4 v[148:149], off
	s_add_i32 m0, s9, 0x2000
	v_lshl_add_u64 v[148:149], s[26:27], 0, v[158:159]
	global_load_lds_dwordx4 v[148:149], off
	s_mov_b32 m0, s50
	v_lshl_add_u64 v[148:149], v[216:217], 0, s[70:71]
	global_load_lds_dwordx4 v[148:149], off
	s_mov_b32 m0, s51
	v_lshl_add_u64 v[148:149], v[218:219], 0, s[70:71]
	global_load_lds_dwordx4 v[148:149], off
	s_waitcnt vmcnt(8) lgkmcnt(0)
	s_setprio 1
	s_barrier
	v_mfma_f32_16x16x32_bf16 v[62:65], v[130:133], v[184:187], v[62:65]
	v_mfma_f32_16x16x32_bf16 v[58:61], v[138:141], v[184:187], v[58:61]
	v_mfma_f32_16x16x32_bf16 v[46:49], v[130:133], v[192:195], v[46:49]
	v_mfma_f32_16x16x32_bf16 v[42:45], v[138:141], v[192:195], v[42:45]
	v_mfma_f32_16x16x32_bf16 v[30:33], v[130:133], v[200:203], v[30:33]
	v_mfma_f32_16x16x32_bf16 v[26:29], v[138:141], v[200:203], v[26:29]
	v_mfma_f32_16x16x32_bf16 v[14:17], v[130:133], v[208:211], v[14:17]
	v_mfma_f32_16x16x32_bf16 v[10:13], v[138:141], v[208:211], v[10:13]
	v_mfma_f32_16x16x32_bf16 v[62:65], v[134:137], v[188:191], v[62:65]
	v_mfma_f32_16x16x32_bf16 v[58:61], v[142:145], v[188:191], v[58:61]
	v_mfma_f32_16x16x32_bf16 v[46:49], v[134:137], v[196:199], v[46:49]
	v_mfma_f32_16x16x32_bf16 v[42:45], v[142:145], v[196:199], v[42:45]
	v_mfma_f32_16x16x32_bf16 v[30:33], v[134:137], v[204:207], v[30:33]
	v_mfma_f32_16x16x32_bf16 v[26:29], v[142:145], v[204:207], v[26:29]
	v_mfma_f32_16x16x32_bf16 v[14:17], v[134:137], v[212:215], v[14:17]
	v_mfma_f32_16x16x32_bf16 v[10:13], v[142:145], v[212:215], v[10:13]
	v_mfma_f32_16x16x32_bf16 v[54:57], v[164:167], v[184:187], v[54:57]
	v_mfma_f32_16x16x32_bf16 v[50:53], v[172:175], v[184:187], v[50:53]
	v_mfma_f32_16x16x32_bf16 v[38:41], v[164:167], v[192:195], v[38:41]
	v_mfma_f32_16x16x32_bf16 v[34:37], v[172:175], v[192:195], v[34:37]
	v_mfma_f32_16x16x32_bf16 v[22:25], v[164:167], v[200:203], v[22:25]
	v_mfma_f32_16x16x32_bf16 v[18:21], v[172:175], v[200:203], v[18:21]
	v_mfma_f32_16x16x32_bf16 v[6:9], v[164:167], v[208:211], v[6:9]
	v_mfma_f32_16x16x32_bf16 v[2:5], v[172:175], v[208:211], v[2:5]
	v_mfma_f32_16x16x32_bf16 v[54:57], v[168:171], v[188:191], v[54:57]
	v_mfma_f32_16x16x32_bf16 v[50:53], v[180:183], v[188:191], v[50:53]
	v_mfma_f32_16x16x32_bf16 v[38:41], v[168:171], v[196:199], v[38:41]
	v_mfma_f32_16x16x32_bf16 v[34:37], v[180:183], v[196:199], v[34:37]
	v_mfma_f32_16x16x32_bf16 v[22:25], v[168:171], v[204:207], v[22:25]
	v_mfma_f32_16x16x32_bf16 v[18:21], v[180:183], v[204:207], v[18:21]
	v_mfma_f32_16x16x32_bf16 v[6:9], v[168:171], v[212:215], v[6:9]
	s_setprio 0
	v_mfma_f32_16x16x32_bf16 v[2:5], v[180:183], v[212:215], v[2:5]
	s_barrier
	s_add_u32 s60, s60, 0x100
	s_addc_u32 s61, s61, 0
	s_add_u32 s28, s28, 0x100
	s_addc_u32 s29, s29, 0
	s_cmp_ge_u32 s75, s17
	s_mov_b32 s26, s75
	s_cbranch_scc0 .LBB0_701
	s_and_b64 vcc, exec, s[14:15]
	s_cbranch_vccz .LBB0_704

.LBB0_846:
	s_add_u32 s9, s96, 0xfffc0080
	s_addc_u32 s38, s97, -1
	s_add_i32 s78, 0, 0x10000
	s_cmp_eq_u32 s75, 12
	s_cselect_b32 vcc_hi, s25, s38
	s_cselect_b32 vcc_lo, s28, s9
	v_add_u32_e32 v148, s78, v145
	s_cselect_b32 s39, s23, s61
	s_cselect_b32 s38, s29, s53
	s_add_i32 s9, 0, 0x14000
	ds_read_b128 v[140:143], v148
	ds_read_b128 v[156:159], v148 offset:1024
	ds_read_b128 v[160:163], v148 offset:2048
	ds_read_b128 v[164:167], v148 offset:3072
	v_add_u32_e32 v148, s9, v145
	ds_read_b128 v[168:171], v148
	ds_read_b128 v[172:175], v148 offset:1024
	ds_read_b128 v[176:179], v148 offset:2048
	ds_read_b128 v[180:183], v148 offset:3072
	v_lshl_add_u64 v[148:149], s[96:97], 0, v[136:137]
	s_add_i32 m0, s46, 0xc000
	ds_read_b128 v[184:187], v147
	ds_read_b128 v[188:191], v147 offset:1024
	ds_read_b128 v[192:195], v147 offset:2048
	ds_read_b128 v[196:199], v147 offset:3072
	ds_read_b128 v[200:203], v147 offset:4096
	ds_read_b128 v[204:207], v147 offset:5120
	ds_read_b128 v[208:211], v147 offset:6144
	ds_read_b128 v[212:215], v147 offset:7168
	global_load_lds_dwordx4 v[148:149], off
	s_add_i32 m0, s46, 0xe000
	v_lshl_add_u64 v[148:149], s[96:97], 0, v[138:139]
	global_load_lds_dwordx4 v[148:149], off
	s_waitcnt vmcnt(8) lgkmcnt(0)
	s_setprio 1
	s_barrier
	v_mfma_f32_16x16x32_bf16 v[126:129], v[140:143], v[184:187], v[126:129]
	v_mfma_f32_16x16x32_bf16 v[118:121], v[160:163], v[184:187], v[118:121]
	v_mfma_f32_16x16x32_bf16 v[110:113], v[140:143], v[192:195], v[110:113]
	v_mfma_f32_16x16x32_bf16 v[102:105], v[160:163], v[192:195], v[102:105]
	v_mfma_f32_16x16x32_bf16 v[94:97], v[140:143], v[200:203], v[94:97]
	v_mfma_f32_16x16x32_bf16 v[86:89], v[160:163], v[200:203], v[86:89]
	v_mfma_f32_16x16x32_bf16 v[78:81], v[140:143], v[208:211], v[78:81]
	v_mfma_f32_16x16x32_bf16 v[70:73], v[160:163], v[208:211], v[70:73]
	v_mfma_f32_16x16x32_bf16 v[126:129], v[156:159], v[188:191], v[126:129]
	v_mfma_f32_16x16x32_bf16 v[118:121], v[164:167], v[188:191], v[118:121]
	v_mfma_f32_16x16x32_bf16 v[110:113], v[156:159], v[196:199], v[110:113]
	v_mfma_f32_16x16x32_bf16 v[102:105], v[164:167], v[196:199], v[102:105]
	v_mfma_f32_16x16x32_bf16 v[94:97], v[156:159], v[204:207], v[94:97]
	v_mfma_f32_16x16x32_bf16 v[86:89], v[164:167], v[204:207], v[86:89]
	v_mfma_f32_16x16x32_bf16 v[78:81], v[156:159], v[212:215], v[78:81]
	v_mfma_f32_16x16x32_bf16 v[70:73], v[164:167], v[212:215], v[70:73]
	v_mfma_f32_16x16x32_bf16 v[122:125], v[168:171], v[184:187], v[122:125]
	v_mfma_f32_16x16x32_bf16 v[114:117], v[176:179], v[184:187], v[114:117]
	v_mfma_f32_16x16x32_bf16 v[106:109], v[168:171], v[192:195], v[106:109]
	v_mfma_f32_16x16x32_bf16 v[98:101], v[176:179], v[192:195], v[98:101]
	v_mfma_f32_16x16x32_bf16 v[90:93], v[168:171], v[200:203], v[90:93]
	v_mfma_f32_16x16x32_bf16 v[82:85], v[176:179], v[200:203], v[82:85]
	v_mfma_f32_16x16x32_bf16 v[74:77], v[168:171], v[208:211], v[74:77]
	v_mfma_f32_16x16x32_bf16 v[66:69], v[176:179], v[208:211], v[66:69]
	v_mfma_f32_16x16x32_bf16 v[122:125], v[172:175], v[188:191], v[122:125]
	v_mfma_f32_16x16x32_bf16 v[114:117], v[180:183], v[188:191], v[114:117]
	v_mfma_f32_16x16x32_bf16 v[106:109], v[172:175], v[196:199], v[106:109]
	v_mfma_f32_16x16x32_bf16 v[98:101], v[180:183], v[196:199], v[98:101]
	v_mfma_f32_16x16x32_bf16 v[90:93], v[172:175], v[204:207], v[90:93]
	v_mfma_f32_16x16x32_bf16 v[82:85], v[180:183], v[204:207], v[82:85]
	v_mfma_f32_16x16x32_bf16 v[74:77], v[172:175], v[212:215], v[74:77]
	s_setprio 0
	v_mfma_f32_16x16x32_bf16 v[66:69], v[180:183], v[212:215], v[66:69]
	s_barrier
	s_add_i32 s78, s78, s45
	v_lshl_add_u64 v[148:149], s[38:39], 0, v[0:1]
	s_mov_b32 m0, s78
	ds_read_b128 v[184:187], v147 offset:16384
	ds_read_b128 v[188:191], v147 offset:17408
	ds_read_b128 v[192:195], v147 offset:18432
	ds_read_b128 v[196:199], v147 offset:19456
	ds_read_b128 v[200:203], v147 offset:20480
	ds_read_b128 v[204:207], v147 offset:21504
	ds_read_b128 v[208:211], v147 offset:22528
	ds_read_b128 v[212:215], v147 offset:23552
	global_load_lds_dwordx4 v[148:149], off
	s_add_i32 m0, s78, 0x2000
	s_add_u32 s78, s38, 0x40000
	v_lshl_add_u64 v[150:151], s[38:39], 0, v[134:135]
	s_addc_u32 s79, s39, 0
	s_add_i32 s9, s9, s45
	global_load_lds_dwordx4 v[150:151], off
	v_lshl_add_u64 v[216:217], s[78:79], 0, v[0:1]
	s_mov_b32 m0, s9
	v_lshl_add_u64 v[218:219], vcc, 0, v[132:133]
	global_load_lds_dwordx4 v[216:217], off
	s_add_i32 m0, s9, 0x2000
	v_lshl_add_u64 v[216:217], s[78:79], 0, v[134:135]
	global_load_lds_dwordx4 v[216:217], off
	s_mov_b32 m0, s46
	v_lshl_add_u64 v[216:217], vcc, 0, v[130:131]
	global_load_lds_dwordx4 v[216:217], off
	s_mov_b32 m0, s47
	s_nop 0
	global_load_lds_dwordx4 v[218:219], off
	s_waitcnt vmcnt(8) lgkmcnt(0)
	s_setprio 1
	s_barrier
	v_mfma_f32_16x16x32_bf16 v[62:65], v[140:143], v[184:187], v[62:65]
	v_mfma_f32_16x16x32_bf16 v[54:57], v[160:163], v[184:187], v[54:57]
	v_mfma_f32_16x16x32_bf16 v[46:49], v[140:143], v[192:195], v[46:49]
	v_mfma_f32_16x16x32_bf16 v[38:41], v[160:163], v[192:195], v[38:41]
	v_mfma_f32_16x16x32_bf16 v[30:33], v[140:143], v[200:203], v[30:33]
	v_mfma_f32_16x16x32_bf16 v[22:25], v[160:163], v[200:203], v[22:25]
	v_mfma_f32_16x16x32_bf16 v[14:17], v[140:143], v[208:211], v[14:17]
	v_mfma_f32_16x16x32_bf16 v[6:9], v[160:163], v[208:211], v[6:9]
	v_mfma_f32_16x16x32_bf16 v[62:65], v[156:159], v[188:191], v[62:65]
	v_mfma_f32_16x16x32_bf16 v[54:57], v[164:167], v[188:191], v[54:57]
	v_mfma_f32_16x16x32_bf16 v[46:49], v[156:159], v[196:199], v[46:49]
	v_mfma_f32_16x16x32_bf16 v[38:41], v[164:167], v[196:199], v[38:41]
	v_mfma_f32_16x16x32_bf16 v[30:33], v[156:159], v[204:207], v[30:33]
	v_mfma_f32_16x16x32_bf16 v[22:25], v[164:167], v[204:207], v[22:25]
	v_mfma_f32_16x16x32_bf16 v[14:17], v[156:159], v[212:215], v[14:17]
	v_mfma_f32_16x16x32_bf16 v[6:9], v[164:167], v[212:215], v[6:9]
	v_mfma_f32_16x16x32_bf16 v[58:61], v[168:171], v[184:187], v[58:61]
	v_mfma_f32_16x16x32_bf16 v[50:53], v[176:179], v[184:187], v[50:53]
	v_mfma_f32_16x16x32_bf16 v[42:45], v[168:171], v[192:195], v[42:45]
	v_mfma_f32_16x16x32_bf16 v[34:37], v[176:179], v[192:195], v[34:37]
	v_mfma_f32_16x16x32_bf16 v[26:29], v[168:171], v[200:203], v[26:29]
	v_mfma_f32_16x16x32_bf16 v[18:21], v[176:179], v[200:203], v[18:21]
	v_mfma_f32_16x16x32_bf16 v[10:13], v[168:171], v[208:211], v[10:13]
	v_mfma_f32_16x16x32_bf16 v[2:5], v[176:179], v[208:211], v[2:5]
	v_mfma_f32_16x16x32_bf16 v[58:61], v[172:175], v[188:191], v[58:61]
	v_mfma_f32_16x16x32_bf16 v[50:53], v[180:183], v[188:191], v[50:53]
	v_mfma_f32_16x16x32_bf16 v[42:45], v[172:175], v[196:199], v[42:45]
	v_mfma_f32_16x16x32_bf16 v[34:37], v[180:183], v[196:199], v[34:37]
	v_mfma_f32_16x16x32_bf16 v[26:29], v[172:175], v[204:207], v[26:29]
	v_mfma_f32_16x16x32_bf16 v[18:21], v[180:183], v[204:207], v[18:21]
	v_mfma_f32_16x16x32_bf16 v[10:13], v[172:175], v[212:215], v[10:13]
	s_setprio 0
	v_mfma_f32_16x16x32_bf16 v[2:5], v[180:183], v[212:215], v[2:5]
	s_barrier
	s_add_i32 s9, 0, 0x18000
	s_add_i32 s83, 0, 0x1c000
	v_add_u32_e32 v164, s9, v145
	v_add_u32_e32 v180, s83, v145
	ds_read_b128 v[140:143], v164
	ds_read_b128 v[156:159], v164 offset:1024
	ds_read_b128 v[160:163], v164 offset:2048
	ds_read_b128 v[164:167], v164 offset:3072
	ds_read_b128 v[168:171], v180
	ds_read_b128 v[172:175], v180 offset:1024
	ds_read_b128 v[176:179], v180 offset:2048
	ds_read_b128 v[180:183], v180 offset:3072
	s_add_u32 s78, vcc_lo, 0x40000
	s_addc_u32 s79, vcc_hi, 0
	s_mov_b32 m0, s48
	v_lshl_add_u64 v[220:221], s[78:79], 0, v[130:131]
	ds_read_b128 v[184:187], v147 offset:32768
	ds_read_b128 v[188:191], v147 offset:33792
	ds_read_b128 v[192:195], v147 offset:34816
	ds_read_b128 v[196:199], v147 offset:35840
	ds_read_b128 v[200:203], v147 offset:36864
	ds_read_b128 v[204:207], v147 offset:37888
	ds_read_b128 v[208:211], v147 offset:38912
	ds_read_b128 v[212:215], v147 offset:39936
	global_load_lds_dwordx4 v[220:221], off
	s_mov_b32 m0, s49
	v_lshl_add_u64 v[220:221], s[78:79], 0, v[132:133]
	global_load_lds_dwordx4 v[220:221], off
	s_waitcnt vmcnt(8) lgkmcnt(0)
	s_setprio 1
	s_barrier
	v_mfma_f32_16x16x32_bf16 v[126:129], v[140:143], v[184:187], v[126:129]
	v_mfma_f32_16x16x32_bf16 v[118:121], v[160:163], v[184:187], v[118:121]
	v_mfma_f32_16x16x32_bf16 v[110:113], v[140:143], v[192:195], v[110:113]
	v_mfma_f32_16x16x32_bf16 v[102:105], v[160:163], v[192:195], v[102:105]
	v_mfma_f32_16x16x32_bf16 v[94:97], v[140:143], v[200:203], v[94:97]
	v_mfma_f32_16x16x32_bf16 v[86:89], v[160:163], v[200:203], v[86:89]
	v_mfma_f32_16x16x32_bf16 v[78:81], v[140:143], v[208:211], v[78:81]
	v_mfma_f32_16x16x32_bf16 v[70:73], v[160:163], v[208:211], v[70:73]
	v_mfma_f32_16x16x32_bf16 v[126:129], v[156:159], v[188:191], v[126:129]
	v_mfma_f32_16x16x32_bf16 v[118:121], v[164:167], v[188:191], v[118:121]
	v_mfma_f32_16x16x32_bf16 v[110:113], v[156:159], v[196:199], v[110:113]
	v_mfma_f32_16x16x32_bf16 v[102:105], v[164:167], v[196:199], v[102:105]
	v_mfma_f32_16x16x32_bf16 v[94:97], v[156:159], v[204:207], v[94:97]
	v_mfma_f32_16x16x32_bf16 v[86:89], v[164:167], v[204:207], v[86:89]
	v_mfma_f32_16x16x32_bf16 v[78:81], v[156:159], v[212:215], v[78:81]
	v_mfma_f32_16x16x32_bf16 v[70:73], v[164:167], v[212:215], v[70:73]
	v_mfma_f32_16x16x32_bf16 v[122:125], v[168:171], v[184:187], v[122:125]
	v_mfma_f32_16x16x32_bf16 v[114:117], v[176:179], v[184:187], v[114:117]
	v_mfma_f32_16x16x32_bf16 v[106:109], v[168:171], v[192:195], v[106:109]
	v_mfma_f32_16x16x32_bf16 v[98:101], v[176:179], v[192:195], v[98:101]
	v_mfma_f32_16x16x32_bf16 v[90:93], v[168:171], v[200:203], v[90:93]
	v_mfma_f32_16x16x32_bf16 v[82:85], v[176:179], v[200:203], v[82:85]
	v_mfma_f32_16x16x32_bf16 v[74:77], v[168:171], v[208:211], v[74:77]
	v_mfma_f32_16x16x32_bf16 v[66:69], v[176:179], v[208:211], v[66:69]
	v_mfma_f32_16x16x32_bf16 v[122:125], v[172:175], v[188:191], v[122:125]
	v_mfma_f32_16x16x32_bf16 v[114:117], v[180:183], v[188:191], v[114:117]
	v_mfma_f32_16x16x32_bf16 v[106:109], v[172:175], v[196:199], v[106:109]
	v_mfma_f32_16x16x32_bf16 v[98:101], v[180:183], v[196:199], v[98:101]
	v_mfma_f32_16x16x32_bf16 v[90:93], v[172:175], v[204:207], v[90:93]
	v_mfma_f32_16x16x32_bf16 v[82:85], v[180:183], v[204:207], v[82:85]
	v_mfma_f32_16x16x32_bf16 v[74:77], v[172:175], v[212:215], v[74:77]
	s_setprio 0
	v_mfma_f32_16x16x32_bf16 v[66:69], v[180:183], v[212:215], v[66:69]
	s_barrier
	s_add_i32 s9, s9, s45
	v_lshl_add_u64 v[148:149], v[148:149], 0, s[70:71]
	s_mov_b32 m0, s9
	ds_read_b128 v[184:187], v147 offset:49152
	ds_read_b128 v[188:191], v147 offset:50176
	ds_read_b128 v[192:195], v147 offset:51200
	ds_read_b128 v[196:199], v147 offset:52224
	ds_read_b128 v[200:203], v147 offset:53248
	ds_read_b128 v[204:207], v147 offset:54272
	ds_read_b128 v[208:211], v147 offset:55296
	ds_read_b128 v[212:215], v147 offset:56320
	global_load_lds_dwordx4 v[148:149], off
	s_add_i32 m0, s9, 0x2000
	s_add_u32 s38, s38, 0x40080
	v_lshl_add_u64 v[148:149], v[150:151], 0, s[70:71]
	s_addc_u32 s39, s39, 0
	s_add_i32 s9, s83, s45
	global_load_lds_dwordx4 v[148:149], off
	s_mov_b32 m0, s9
	v_lshl_add_u64 v[148:149], s[38:39], 0, v[0:1]
	global_load_lds_dwordx4 v[148:149], off
	s_add_i32 m0, s9, 0x2000
	v_lshl_add_u64 v[148:149], s[38:39], 0, v[134:135]
	global_load_lds_dwordx4 v[148:149], off
	s_mov_b32 m0, s50
	v_lshl_add_u64 v[148:149], v[216:217], 0, s[70:71]
	global_load_lds_dwordx4 v[148:149], off
	s_mov_b32 m0, s51
	v_lshl_add_u64 v[148:149], v[218:219], 0, s[70:71]
	global_load_lds_dwordx4 v[148:149], off
	s_waitcnt vmcnt(8) lgkmcnt(0)
	s_setprio 1
	s_barrier
	v_mfma_f32_16x16x32_bf16 v[62:65], v[140:143], v[184:187], v[62:65]
	v_mfma_f32_16x16x32_bf16 v[54:57], v[160:163], v[184:187], v[54:57]
	v_mfma_f32_16x16x32_bf16 v[46:49], v[140:143], v[192:195], v[46:49]
	v_mfma_f32_16x16x32_bf16 v[38:41], v[160:163], v[192:195], v[38:41]
	v_mfma_f32_16x16x32_bf16 v[30:33], v[140:143], v[200:203], v[30:33]
	v_mfma_f32_16x16x32_bf16 v[22:25], v[160:163], v[200:203], v[22:25]
	v_mfma_f32_16x16x32_bf16 v[14:17], v[140:143], v[208:211], v[14:17]
	v_mfma_f32_16x16x32_bf16 v[6:9], v[160:163], v[208:211], v[6:9]
	v_mfma_f32_16x16x32_bf16 v[62:65], v[156:159], v[188:191], v[62:65]
	v_mfma_f32_16x16x32_bf16 v[54:57], v[164:167], v[188:191], v[54:57]
	v_mfma_f32_16x16x32_bf16 v[46:49], v[156:159], v[196:199], v[46:49]
	v_mfma_f32_16x16x32_bf16 v[38:41], v[164:167], v[196:199], v[38:41]
	v_mfma_f32_16x16x32_bf16 v[30:33], v[156:159], v[204:207], v[30:33]
	v_mfma_f32_16x16x32_bf16 v[22:25], v[164:167], v[204:207], v[22:25]
	v_mfma_f32_16x16x32_bf16 v[14:17], v[156:159], v[212:215], v[14:17]
	v_mfma_f32_16x16x32_bf16 v[6:9], v[164:167], v[212:215], v[6:9]
	v_mfma_f32_16x16x32_bf16 v[58:61], v[168:171], v[184:187], v[58:61]
	v_mfma_f32_16x16x32_bf16 v[50:53], v[176:179], v[184:187], v[50:53]
	v_mfma_f32_16x16x32_bf16 v[42:45], v[168:171], v[192:195], v[42:45]
	v_mfma_f32_16x16x32_bf16 v[34:37], v[176:179], v[192:195], v[34:37]
	v_mfma_f32_16x16x32_bf16 v[26:29], v[168:171], v[200:203], v[26:29]
	v_mfma_f32_16x16x32_bf16 v[18:21], v[176:179], v[200:203], v[18:21]
	v_mfma_f32_16x16x32_bf16 v[10:13], v[168:171], v[208:211], v[10:13]
	v_mfma_f32_16x16x32_bf16 v[2:5], v[176:179], v[208:211], v[2:5]
	v_mfma_f32_16x16x32_bf16 v[58:61], v[172:175], v[188:191], v[58:61]
	v_mfma_f32_16x16x32_bf16 v[50:53], v[180:183], v[188:191], v[50:53]
	v_mfma_f32_16x16x32_bf16 v[42:45], v[172:175], v[196:199], v[42:45]
	v_mfma_f32_16x16x32_bf16 v[34:37], v[180:183], v[196:199], v[34:37]
	v_mfma_f32_16x16x32_bf16 v[26:29], v[172:175], v[204:207], v[26:29]
	v_mfma_f32_16x16x32_bf16 v[18:21], v[180:183], v[204:207], v[18:21]
	v_mfma_f32_16x16x32_bf16 v[10:13], v[172:175], v[212:215], v[10:13]
	s_setprio 0
	v_mfma_f32_16x16x32_bf16 v[2:5], v[180:183], v[212:215], v[2:5]
	s_barrier
	s_add_i32 s75, s75, 2
	s_add_u32 s96, s96, 0x100
	s_addc_u32 s97, s97, 0
	s_add_u32 s53, s53, 0x100
	s_addc_u32 s61, s61, 0
	s_cmp_gt_u32 s75, 13
	s_cbranch_scc0 .LBB0_846
	s_and_b64 vcc, exec, s[14:15]
	s_cbranch_vccz .LBB0_849
	s_barrier

.LBB0_950:
	s_add_i32 s9, s26, 2
	s_add_u32 s60, s38, 0x100
	s_addc_u32 s61, s39, 0
	s_add_i32 s78, 0, 0x10000
	s_cmp_eq_u32 s29, s26
	s_cselect_b32 s73, s25, s61
	s_cselect_b32 s72, s24, s60
	s_cselect_b32 s27, s37, vcc_hi
	s_cselect_b32 s26, s36, vcc_lo
	s_add_i32 s79, 0, 0x14000
	v_add_u32_e32 v156, s78, v177
	v_add_u32_e32 v172, s79, v177
	ds_read_b128 v[140:143], v156
	ds_read_b128 v[144:147], v156 offset:1024
	ds_read_b128 v[148:151], v156 offset:2048
	ds_read_b128 v[156:159], v156 offset:3072
	ds_read_b128 v[160:163], v172
	ds_read_b128 v[164:167], v172 offset:1024
	ds_read_b128 v[168:171], v172 offset:2048
	ds_read_b128 v[172:175], v172 offset:3072
	v_lshl_add_u64 v[212:213], s[38:39], 0, v[136:137]
	s_add_i32 m0, s50, 0xc000
	ds_read_b128 v[180:183], v179
	ds_read_b128 v[184:187], v179 offset:1024
	ds_read_b128 v[188:191], v179 offset:2048
	ds_read_b128 v[192:195], v179 offset:3072
	ds_read_b128 v[196:199], v179 offset:4096
	ds_read_b128 v[200:203], v179 offset:5120
	ds_read_b128 v[204:207], v179 offset:6144
	ds_read_b128 v[208:211], v179 offset:7168
	global_load_lds_dwordx4 v[212:213], off
	s_add_i32 m0, s50, 0xe000
	v_lshl_add_u64 v[212:213], s[38:39], 0, v[138:139]
	global_load_lds_dwordx4 v[212:213], off
	s_waitcnt vmcnt(8) lgkmcnt(0)
	s_setprio 1
	s_barrier
	v_mfma_f32_16x16x32_bf16 v[126:129], v[140:143], v[180:183], v[126:129]
	v_mfma_f32_16x16x32_bf16 v[122:125], v[148:151], v[180:183], v[122:125]
	v_mfma_f32_16x16x32_bf16 v[110:113], v[140:143], v[188:191], v[110:113]
	v_mfma_f32_16x16x32_bf16 v[106:109], v[148:151], v[188:191], v[106:109]
	v_mfma_f32_16x16x32_bf16 v[94:97], v[140:143], v[196:199], v[94:97]
	v_mfma_f32_16x16x32_bf16 v[90:93], v[148:151], v[196:199], v[90:93]
	v_mfma_f32_16x16x32_bf16 v[78:81], v[140:143], v[204:207], v[78:81]
	v_mfma_f32_16x16x32_bf16 v[74:77], v[148:151], v[204:207], v[74:77]
	v_mfma_f32_16x16x32_bf16 v[126:129], v[144:147], v[184:187], v[126:129]
	v_mfma_f32_16x16x32_bf16 v[122:125], v[156:159], v[184:187], v[122:125]
	v_mfma_f32_16x16x32_bf16 v[110:113], v[144:147], v[192:195], v[110:113]
	v_mfma_f32_16x16x32_bf16 v[106:109], v[156:159], v[192:195], v[106:109]
	v_mfma_f32_16x16x32_bf16 v[94:97], v[144:147], v[200:203], v[94:97]
	v_mfma_f32_16x16x32_bf16 v[90:93], v[156:159], v[200:203], v[90:93]
	v_mfma_f32_16x16x32_bf16 v[78:81], v[144:147], v[208:211], v[78:81]
	v_mfma_f32_16x16x32_bf16 v[74:77], v[156:159], v[208:211], v[74:77]
	v_mfma_f32_16x16x32_bf16 v[118:121], v[160:163], v[180:183], v[118:121]
	v_mfma_f32_16x16x32_bf16 v[114:117], v[168:171], v[180:183], v[114:117]
	v_mfma_f32_16x16x32_bf16 v[102:105], v[160:163], v[188:191], v[102:105]
	v_mfma_f32_16x16x32_bf16 v[98:101], v[168:171], v[188:191], v[98:101]
	v_mfma_f32_16x16x32_bf16 v[86:89], v[160:163], v[196:199], v[86:89]
	v_mfma_f32_16x16x32_bf16 v[82:85], v[168:171], v[196:199], v[82:85]
	v_mfma_f32_16x16x32_bf16 v[70:73], v[160:163], v[204:207], v[70:73]
	v_mfma_f32_16x16x32_bf16 v[66:69], v[168:171], v[204:207], v[66:69]
	v_mfma_f32_16x16x32_bf16 v[118:121], v[164:167], v[184:187], v[118:121]
	v_mfma_f32_16x16x32_bf16 v[114:117], v[172:175], v[184:187], v[114:117]
	v_mfma_f32_16x16x32_bf16 v[102:105], v[164:167], v[192:195], v[102:105]
	v_mfma_f32_16x16x32_bf16 v[98:101], v[172:175], v[192:195], v[98:101]
	v_mfma_f32_16x16x32_bf16 v[86:89], v[164:167], v[200:203], v[86:89]
	v_mfma_f32_16x16x32_bf16 v[82:85], v[172:175], v[200:203], v[82:85]
	v_mfma_f32_16x16x32_bf16 v[70:73], v[164:167], v[208:211], v[70:73]
	s_setprio 0
	v_mfma_f32_16x16x32_bf16 v[66:69], v[172:175], v[208:211], v[66:69]
	s_barrier
	s_add_i32 s38, s78, s49
	v_lshl_add_u64 v[212:213], s[26:27], 0, v[0:1]
	s_mov_b32 m0, s38
	ds_read_b128 v[180:183], v179 offset:16384
	ds_read_b128 v[184:187], v179 offset:17408
	ds_read_b128 v[188:191], v179 offset:18432
	ds_read_b128 v[192:195], v179 offset:19456
	ds_read_b128 v[196:199], v179 offset:20480
	ds_read_b128 v[200:203], v179 offset:21504
	ds_read_b128 v[204:207], v179 offset:22528
	ds_read_b128 v[208:211], v179 offset:23552
	global_load_lds_dwordx4 v[212:213], off
	s_add_i32 m0, s38, 0x2000
	s_add_u32 s38, s26, 0xb0000
	v_lshl_add_u64 v[214:215], s[26:27], 0, v[134:135]
	s_addc_u32 s39, s27, 0
	s_add_i32 s78, s79, s49
	global_load_lds_dwordx4 v[214:215], off
	v_lshl_add_u64 v[216:217], s[38:39], 0, v[0:1]
	s_mov_b32 m0, s78
	v_lshl_add_u64 v[218:219], s[72:73], 0, v[132:133]
	global_load_lds_dwordx4 v[216:217], off
	s_add_i32 m0, s78, 0x2000
	v_lshl_add_u64 v[216:217], s[38:39], 0, v[134:135]
	global_load_lds_dwordx4 v[216:217], off
	s_mov_b32 m0, s50
	v_lshl_add_u64 v[216:217], s[72:73], 0, v[130:131]
	global_load_lds_dwordx4 v[216:217], off
	s_mov_b32 m0, s51
	s_nop 0
	global_load_lds_dwordx4 v[218:219], off
	s_waitcnt vmcnt(8) lgkmcnt(0)
	s_setprio 1
	s_barrier
	v_mfma_f32_16x16x32_bf16 v[62:65], v[140:143], v[180:183], v[62:65]
	v_mfma_f32_16x16x32_bf16 v[58:61], v[148:151], v[180:183], v[58:61]
	v_mfma_f32_16x16x32_bf16 v[46:49], v[140:143], v[188:191], v[46:49]
	v_mfma_f32_16x16x32_bf16 v[42:45], v[148:151], v[188:191], v[42:45]
	v_mfma_f32_16x16x32_bf16 v[30:33], v[140:143], v[196:199], v[30:33]
	v_mfma_f32_16x16x32_bf16 v[26:29], v[148:151], v[196:199], v[26:29]
	v_mfma_f32_16x16x32_bf16 v[14:17], v[140:143], v[204:207], v[14:17]
	v_mfma_f32_16x16x32_bf16 v[10:13], v[148:151], v[204:207], v[10:13]
	v_mfma_f32_16x16x32_bf16 v[62:65], v[144:147], v[184:187], v[62:65]
	v_mfma_f32_16x16x32_bf16 v[58:61], v[156:159], v[184:187], v[58:61]
	v_mfma_f32_16x16x32_bf16 v[46:49], v[144:147], v[192:195], v[46:49]
	v_mfma_f32_16x16x32_bf16 v[42:45], v[156:159], v[192:195], v[42:45]
	v_mfma_f32_16x16x32_bf16 v[30:33], v[144:147], v[200:203], v[30:33]
	v_mfma_f32_16x16x32_bf16 v[26:29], v[156:159], v[200:203], v[26:29]
	v_mfma_f32_16x16x32_bf16 v[14:17], v[144:147], v[208:211], v[14:17]
	v_mfma_f32_16x16x32_bf16 v[10:13], v[156:159], v[208:211], v[10:13]
	v_mfma_f32_16x16x32_bf16 v[54:57], v[160:163], v[180:183], v[54:57]
	v_mfma_f32_16x16x32_bf16 v[50:53], v[168:171], v[180:183], v[50:53]
	v_mfma_f32_16x16x32_bf16 v[38:41], v[160:163], v[188:191], v[38:41]
	v_mfma_f32_16x16x32_bf16 v[34:37], v[168:171], v[188:191], v[34:37]
	v_mfma_f32_16x16x32_bf16 v[22:25], v[160:163], v[196:199], v[22:25]
	v_mfma_f32_16x16x32_bf16 v[18:21], v[168:171], v[196:199], v[18:21]
	v_mfma_f32_16x16x32_bf16 v[6:9], v[160:163], v[204:207], v[6:9]
	v_mfma_f32_16x16x32_bf16 v[2:5], v[168:171], v[204:207], v[2:5]
	v_mfma_f32_16x16x32_bf16 v[54:57], v[164:167], v[184:187], v[54:57]
	v_mfma_f32_16x16x32_bf16 v[50:53], v[172:175], v[184:187], v[50:53]
	v_mfma_f32_16x16x32_bf16 v[38:41], v[164:167], v[192:195], v[38:41]
	v_mfma_f32_16x16x32_bf16 v[34:37], v[172:175], v[192:195], v[34:37]
	v_mfma_f32_16x16x32_bf16 v[22:25], v[164:167], v[200:203], v[22:25]
	v_mfma_f32_16x16x32_bf16 v[18:21], v[172:175], v[200:203], v[18:21]
	v_mfma_f32_16x16x32_bf16 v[6:9], v[164:167], v[208:211], v[6:9]
	s_setprio 0
	v_mfma_f32_16x16x32_bf16 v[2:5], v[172:175], v[208:211], v[2:5]
	s_barrier
	s_add_i32 s78, 0, 0x18000
	s_add_i32 s79, 0, 0x1c000
	v_add_u32_e32 v156, s78, v177
	v_add_u32_e32 v172, s79, v177
	ds_read_b128 v[140:143], v156
	ds_read_b128 v[144:147], v156 offset:1024
	ds_read_b128 v[148:151], v156 offset:2048
	ds_read_b128 v[156:159], v156 offset:3072
	ds_read_b128 v[160:163], v172
	ds_read_b128 v[164:167], v172 offset:1024
	ds_read_b128 v[168:171], v172 offset:2048
	ds_read_b128 v[172:175], v172 offset:3072
	s_add_u32 s38, s72, 0xb0000
	s_addc_u32 s39, s73, 0
	s_mov_b32 m0, s52
	v_lshl_add_u64 v[220:221], s[38:39], 0, v[130:131]
	ds_read_b128 v[180:183], v179 offset:32768
	ds_read_b128 v[184:187], v179 offset:33792
	ds_read_b128 v[188:191], v179 offset:34816
	ds_read_b128 v[192:195], v179 offset:35840
	ds_read_b128 v[196:199], v179 offset:36864
	ds_read_b128 v[200:203], v179 offset:37888
	ds_read_b128 v[204:207], v179 offset:38912
	ds_read_b128 v[208:211], v179 offset:39936
	global_load_lds_dwordx4 v[220:221], off
	s_mov_b32 m0, s53
	v_lshl_add_u64 v[220:221], s[38:39], 0, v[132:133]
	global_load_lds_dwordx4 v[220:221], off
	s_waitcnt vmcnt(8) lgkmcnt(0)
	s_setprio 1
	s_barrier
	v_mfma_f32_16x16x32_bf16 v[126:129], v[140:143], v[180:183], v[126:129]
	v_mfma_f32_16x16x32_bf16 v[122:125], v[148:151], v[180:183], v[122:125]
	v_mfma_f32_16x16x32_bf16 v[110:113], v[140:143], v[188:191], v[110:113]
	v_mfma_f32_16x16x32_bf16 v[106:109], v[148:151], v[188:191], v[106:109]
	v_mfma_f32_16x16x32_bf16 v[94:97], v[140:143], v[196:199], v[94:97]
	v_mfma_f32_16x16x32_bf16 v[90:93], v[148:151], v[196:199], v[90:93]
	v_mfma_f32_16x16x32_bf16 v[78:81], v[140:143], v[204:207], v[78:81]
	v_mfma_f32_16x16x32_bf16 v[74:77], v[148:151], v[204:207], v[74:77]
	v_mfma_f32_16x16x32_bf16 v[126:129], v[144:147], v[184:187], v[126:129]
	v_mfma_f32_16x16x32_bf16 v[122:125], v[156:159], v[184:187], v[122:125]
	v_mfma_f32_16x16x32_bf16 v[110:113], v[144:147], v[192:195], v[110:113]
	v_mfma_f32_16x16x32_bf16 v[106:109], v[156:159], v[192:195], v[106:109]
	v_mfma_f32_16x16x32_bf16 v[94:97], v[144:147], v[200:203], v[94:97]
	v_mfma_f32_16x16x32_bf16 v[90:93], v[156:159], v[200:203], v[90:93]
	v_mfma_f32_16x16x32_bf16 v[78:81], v[144:147], v[208:211], v[78:81]
	v_mfma_f32_16x16x32_bf16 v[74:77], v[156:159], v[208:211], v[74:77]
	v_mfma_f32_16x16x32_bf16 v[118:121], v[160:163], v[180:183], v[118:121]
	v_mfma_f32_16x16x32_bf16 v[114:117], v[168:171], v[180:183], v[114:117]
	v_mfma_f32_16x16x32_bf16 v[102:105], v[160:163], v[188:191], v[102:105]
	v_mfma_f32_16x16x32_bf16 v[98:101], v[168:171], v[188:191], v[98:101]
	v_mfma_f32_16x16x32_bf16 v[86:89], v[160:163], v[196:199], v[86:89]
	v_mfma_f32_16x16x32_bf16 v[82:85], v[168:171], v[196:199], v[82:85]
	v_mfma_f32_16x16x32_bf16 v[70:73], v[160:163], v[204:207], v[70:73]
	v_mfma_f32_16x16x32_bf16 v[66:69], v[168:171], v[204:207], v[66:69]
	v_mfma_f32_16x16x32_bf16 v[118:121], v[164:167], v[184:187], v[118:121]
	v_mfma_f32_16x16x32_bf16 v[114:117], v[172:175], v[184:187], v[114:117]
	v_mfma_f32_16x16x32_bf16 v[102:105], v[164:167], v[192:195], v[102:105]
	v_mfma_f32_16x16x32_bf16 v[98:101], v[172:175], v[192:195], v[98:101]
	v_mfma_f32_16x16x32_bf16 v[86:89], v[164:167], v[200:203], v[86:89]
	v_mfma_f32_16x16x32_bf16 v[82:85], v[172:175], v[200:203], v[82:85]
	v_mfma_f32_16x16x32_bf16 v[70:73], v[164:167], v[208:211], v[70:73]
	s_setprio 0
	v_mfma_f32_16x16x32_bf16 v[66:69], v[172:175], v[208:211], v[66:69]
	s_barrier
	s_add_i32 s38, s78, s49
	v_lshl_add_u64 v[212:213], v[212:213], 0, s[70:71]
	s_mov_b32 m0, s38
	ds_read_b128 v[180:183], v179 offset:49152
	ds_read_b128 v[184:187], v179 offset:50176
	ds_read_b128 v[188:191], v179 offset:51200
	ds_read_b128 v[192:195], v179 offset:52224
	ds_read_b128 v[196:199], v179 offset:53248
	ds_read_b128 v[200:203], v179 offset:54272
	ds_read_b128 v[204:207], v179 offset:55296
	ds_read_b128 v[208:211], v179 offset:56320
	global_load_lds_dwordx4 v[212:213], off
	s_add_i32 m0, s38, 0x2000
	s_add_u32 s26, s26, 0xb0080
	v_lshl_add_u64 v[212:213], v[214:215], 0, s[70:71]
	s_addc_u32 s27, s27, 0
	s_add_i32 s38, s79, s49
	global_load_lds_dwordx4 v[212:213], off
	s_mov_b32 m0, s38
	v_lshl_add_u64 v[212:213], s[26:27], 0, v[0:1]
	global_load_lds_dwordx4 v[212:213], off
	s_add_i32 m0, s38, 0x2000
	v_lshl_add_u64 v[212:213], s[26:27], 0, v[134:135]
	global_load_lds_dwordx4 v[212:213], off
	s_mov_b32 m0, s74
	v_lshl_add_u64 v[212:213], v[216:217], 0, s[70:71]
	global_load_lds_dwordx4 v[212:213], off
	s_mov_b32 m0, s75
	v_lshl_add_u64 v[212:213], v[218:219], 0, s[70:71]
	global_load_lds_dwordx4 v[212:213], off
	s_waitcnt vmcnt(8) lgkmcnt(0)
	s_setprio 1
	s_barrier
	v_mfma_f32_16x16x32_bf16 v[62:65], v[140:143], v[180:183], v[62:65]
	v_mfma_f32_16x16x32_bf16 v[58:61], v[148:151], v[180:183], v[58:61]
	v_mfma_f32_16x16x32_bf16 v[46:49], v[140:143], v[188:191], v[46:49]
	v_mfma_f32_16x16x32_bf16 v[42:45], v[148:151], v[188:191], v[42:45]
	v_mfma_f32_16x16x32_bf16 v[30:33], v[140:143], v[196:199], v[30:33]
	v_mfma_f32_16x16x32_bf16 v[26:29], v[148:151], v[196:199], v[26:29]
	v_mfma_f32_16x16x32_bf16 v[14:17], v[140:143], v[204:207], v[14:17]
	v_mfma_f32_16x16x32_bf16 v[10:13], v[148:151], v[204:207], v[10:13]
	v_mfma_f32_16x16x32_bf16 v[62:65], v[144:147], v[184:187], v[62:65]
	v_mfma_f32_16x16x32_bf16 v[58:61], v[156:159], v[184:187], v[58:61]
	v_mfma_f32_16x16x32_bf16 v[46:49], v[144:147], v[192:195], v[46:49]
	v_mfma_f32_16x16x32_bf16 v[42:45], v[156:159], v[192:195], v[42:45]
	v_mfma_f32_16x16x32_bf16 v[30:33], v[144:147], v[200:203], v[30:33]
	v_mfma_f32_16x16x32_bf16 v[26:29], v[156:159], v[200:203], v[26:29]
	v_mfma_f32_16x16x32_bf16 v[14:17], v[144:147], v[208:211], v[14:17]
	v_mfma_f32_16x16x32_bf16 v[10:13], v[156:159], v[208:211], v[10:13]
	v_mfma_f32_16x16x32_bf16 v[54:57], v[160:163], v[180:183], v[54:57]
	v_mfma_f32_16x16x32_bf16 v[50:53], v[168:171], v[180:183], v[50:53]
	v_mfma_f32_16x16x32_bf16 v[38:41], v[160:163], v[188:191], v[38:41]
	v_mfma_f32_16x16x32_bf16 v[34:37], v[168:171], v[188:191], v[34:37]
	v_mfma_f32_16x16x32_bf16 v[22:25], v[160:163], v[196:199], v[22:25]
	v_mfma_f32_16x16x32_bf16 v[18:21], v[168:171], v[196:199], v[18:21]
	v_mfma_f32_16x16x32_bf16 v[6:9], v[160:163], v[204:207], v[6:9]
	v_mfma_f32_16x16x32_bf16 v[2:5], v[168:171], v[204:207], v[2:5]
	v_mfma_f32_16x16x32_bf16 v[54:57], v[164:167], v[184:187], v[54:57]
	v_mfma_f32_16x16x32_bf16 v[50:53], v[172:175], v[184:187], v[50:53]
	v_mfma_f32_16x16x32_bf16 v[38:41], v[164:167], v[192:195], v[38:41]
	v_mfma_f32_16x16x32_bf16 v[34:37], v[172:175], v[192:195], v[34:37]
	v_mfma_f32_16x16x32_bf16 v[22:25], v[164:167], v[200:203], v[22:25]
	v_mfma_f32_16x16x32_bf16 v[18:21], v[172:175], v[200:203], v[18:21]
	v_mfma_f32_16x16x32_bf16 v[6:9], v[164:167], v[208:211], v[6:9]
	s_setprio 0
	v_mfma_f32_16x16x32_bf16 v[2:5], v[172:175], v[208:211], v[2:5]
	s_barrier
	s_add_u32 vcc_lo, vcc_lo, 0x100
	s_addc_u32 vcc_hi, vcc_hi, 0
	s_cmp_ge_u32 s9, s28
	s_mov_b64 s[38:39], s[60:61]
	s_mov_b32 s26, s9
	s_cbranch_scc0 .LBB0_950
	s_and_b64 vcc, exec, s[22:23]
	s_cbranch_vccz .LBB0_953

.LBB0_1000:
	s_add_i32 s9, s26, 2
	s_add_u32 s60, s38, 0x100
	s_addc_u32 s61, s39, 0
	s_add_i32 s78, 0, 0x10000
	s_cmp_eq_u32 s29, s26
	s_cselect_b32 s73, s25, s61
	s_cselect_b32 s72, s24, s60
	v_add_u32_e32 v148, s78, v251
	s_cselect_b32 s27, s37, vcc_hi
	s_cselect_b32 s26, s36, vcc_lo
	s_add_i32 s79, 0, 0x14000
	ds_read_b128 v[140:143], v148
	ds_read_b128 v[144:147], v148 offset:1024
	ds_read_b128 v[156:159], v148 offset:2048
	ds_read_b128 v[160:163], v148 offset:3072
	v_add_u32_e32 v148, s79, v251
	ds_read_b128 v[164:167], v148
	ds_read_b128 v[168:171], v148 offset:1024
	ds_read_b128 v[172:175], v148 offset:2048
	ds_read_b128 v[176:179], v148 offset:3072
	v_lshl_add_u64 v[148:149], s[38:39], 0, v[136:137]
	s_add_i32 m0, s50, 0xc000
	ds_read_b128 v[180:183], v253
	ds_read_b128 v[184:187], v253 offset:1024
	ds_read_b128 v[188:191], v253 offset:2048
	ds_read_b128 v[192:195], v253 offset:3072
	ds_read_b128 v[196:199], v253 offset:4096
	ds_read_b128 v[200:203], v253 offset:5120
	ds_read_b128 v[204:207], v253 offset:6144
	ds_read_b128 v[208:211], v253 offset:7168
	global_load_lds_dwordx4 v[148:149], off
	s_add_i32 m0, s50, 0xe000
	v_lshl_add_u64 v[148:149], s[38:39], 0, v[138:139]
	global_load_lds_dwordx4 v[148:149], off
	s_waitcnt vmcnt(8) lgkmcnt(0)
	s_setprio 1
	s_barrier
	v_mfma_f32_16x16x32_bf16 v[126:129], v[140:143], v[180:183], v[126:129]
	v_mfma_f32_16x16x32_bf16 v[122:125], v[156:159], v[180:183], v[122:125]
	v_mfma_f32_16x16x32_bf16 v[110:113], v[140:143], v[188:191], v[110:113]
	v_mfma_f32_16x16x32_bf16 v[106:109], v[156:159], v[188:191], v[106:109]
	v_mfma_f32_16x16x32_bf16 v[94:97], v[140:143], v[196:199], v[94:97]
	v_mfma_f32_16x16x32_bf16 v[90:93], v[156:159], v[196:199], v[90:93]
	v_mfma_f32_16x16x32_bf16 v[78:81], v[140:143], v[204:207], v[78:81]
	v_mfma_f32_16x16x32_bf16 v[74:77], v[156:159], v[204:207], v[74:77]
	v_mfma_f32_16x16x32_bf16 v[126:129], v[144:147], v[184:187], v[126:129]
	v_mfma_f32_16x16x32_bf16 v[122:125], v[160:163], v[184:187], v[122:125]
	v_mfma_f32_16x16x32_bf16 v[110:113], v[144:147], v[192:195], v[110:113]
	v_mfma_f32_16x16x32_bf16 v[106:109], v[160:163], v[192:195], v[106:109]
	v_mfma_f32_16x16x32_bf16 v[94:97], v[144:147], v[200:203], v[94:97]
	v_mfma_f32_16x16x32_bf16 v[90:93], v[160:163], v[200:203], v[90:93]
	v_mfma_f32_16x16x32_bf16 v[78:81], v[144:147], v[208:211], v[78:81]
	v_mfma_f32_16x16x32_bf16 v[74:77], v[160:163], v[208:211], v[74:77]
	v_mfma_f32_16x16x32_bf16 v[118:121], v[164:167], v[180:183], v[118:121]
	v_mfma_f32_16x16x32_bf16 v[114:117], v[172:175], v[180:183], v[114:117]
	v_mfma_f32_16x16x32_bf16 v[102:105], v[164:167], v[188:191], v[102:105]
	v_mfma_f32_16x16x32_bf16 v[98:101], v[172:175], v[188:191], v[98:101]
	v_mfma_f32_16x16x32_bf16 v[86:89], v[164:167], v[196:199], v[86:89]
	v_mfma_f32_16x16x32_bf16 v[82:85], v[172:175], v[196:199], v[82:85]
	v_mfma_f32_16x16x32_bf16 v[70:73], v[164:167], v[204:207], v[70:73]
	v_mfma_f32_16x16x32_bf16 v[66:69], v[172:175], v[204:207], v[66:69]
	v_mfma_f32_16x16x32_bf16 v[118:121], v[168:171], v[184:187], v[118:121]
	v_mfma_f32_16x16x32_bf16 v[114:117], v[176:179], v[184:187], v[114:117]
	v_mfma_f32_16x16x32_bf16 v[102:105], v[168:171], v[192:195], v[102:105]
	v_mfma_f32_16x16x32_bf16 v[98:101], v[176:179], v[192:195], v[98:101]
	v_mfma_f32_16x16x32_bf16 v[86:89], v[168:171], v[200:203], v[86:89]
	v_mfma_f32_16x16x32_bf16 v[82:85], v[176:179], v[200:203], v[82:85]
	v_mfma_f32_16x16x32_bf16 v[70:73], v[168:171], v[208:211], v[70:73]
	s_setprio 0
	v_mfma_f32_16x16x32_bf16 v[66:69], v[176:179], v[208:211], v[66:69]
	s_barrier
	s_add_i32 s38, s78, s49
	v_lshl_add_u64 v[148:149], s[26:27], 0, v[0:1]
	s_mov_b32 m0, s38
	ds_read_b128 v[180:183], v253 offset:16384
	ds_read_b128 v[184:187], v253 offset:17408
	ds_read_b128 v[188:191], v253 offset:18432
	ds_read_b128 v[192:195], v253 offset:19456
	ds_read_b128 v[196:199], v253 offset:20480
	ds_read_b128 v[200:203], v253 offset:21504
	ds_read_b128 v[204:207], v253 offset:22528
	ds_read_b128 v[208:211], v253 offset:23552
	global_load_lds_dwordx4 v[148:149], off
	s_add_i32 m0, s38, 0x2000
	s_add_u32 s38, s26, 0xb0000
	v_lshl_add_u64 v[150:151], s[26:27], 0, v[134:135]
	s_addc_u32 s39, s27, 0
	s_add_i32 s78, s79, s49
	global_load_lds_dwordx4 v[150:151], off
	v_lshl_add_u64 v[212:213], s[38:39], 0, v[0:1]
	s_mov_b32 m0, s78
	v_lshl_add_u64 v[214:215], s[72:73], 0, v[132:133]
	global_load_lds_dwordx4 v[212:213], off
	s_add_i32 m0, s78, 0x2000
	v_lshl_add_u64 v[212:213], s[38:39], 0, v[134:135]
	global_load_lds_dwordx4 v[212:213], off
	s_mov_b32 m0, s50
	v_lshl_add_u64 v[212:213], s[72:73], 0, v[130:131]
	global_load_lds_dwordx4 v[212:213], off
	s_mov_b32 m0, s51
	s_nop 0
	global_load_lds_dwordx4 v[214:215], off
	s_waitcnt vmcnt(8) lgkmcnt(0)
	s_setprio 1
	s_barrier
	v_mfma_f32_16x16x32_bf16 v[62:65], v[140:143], v[180:183], v[62:65]
	v_mfma_f32_16x16x32_bf16 v[58:61], v[156:159], v[180:183], v[58:61]
	v_mfma_f32_16x16x32_bf16 v[46:49], v[140:143], v[188:191], v[46:49]
	v_mfma_f32_16x16x32_bf16 v[42:45], v[156:159], v[188:191], v[42:45]
	v_mfma_f32_16x16x32_bf16 v[30:33], v[140:143], v[196:199], v[30:33]
	v_mfma_f32_16x16x32_bf16 v[26:29], v[156:159], v[196:199], v[26:29]
	v_mfma_f32_16x16x32_bf16 v[14:17], v[140:143], v[204:207], v[14:17]
	v_mfma_f32_16x16x32_bf16 v[10:13], v[156:159], v[204:207], v[10:13]
	v_mfma_f32_16x16x32_bf16 v[62:65], v[144:147], v[184:187], v[62:65]
	v_mfma_f32_16x16x32_bf16 v[58:61], v[160:163], v[184:187], v[58:61]
	v_mfma_f32_16x16x32_bf16 v[46:49], v[144:147], v[192:195], v[46:49]
	v_mfma_f32_16x16x32_bf16 v[42:45], v[160:163], v[192:195], v[42:45]
	v_mfma_f32_16x16x32_bf16 v[30:33], v[144:147], v[200:203], v[30:33]
	v_mfma_f32_16x16x32_bf16 v[26:29], v[160:163], v[200:203], v[26:29]
	v_mfma_f32_16x16x32_bf16 v[14:17], v[144:147], v[208:211], v[14:17]
	v_mfma_f32_16x16x32_bf16 v[10:13], v[160:163], v[208:211], v[10:13]
	v_mfma_f32_16x16x32_bf16 v[54:57], v[164:167], v[180:183], v[54:57]
	v_mfma_f32_16x16x32_bf16 v[50:53], v[172:175], v[180:183], v[50:53]
	v_mfma_f32_16x16x32_bf16 v[38:41], v[164:167], v[188:191], v[38:41]
	v_mfma_f32_16x16x32_bf16 v[34:37], v[172:175], v[188:191], v[34:37]
	v_mfma_f32_16x16x32_bf16 v[22:25], v[164:167], v[196:199], v[22:25]
	v_mfma_f32_16x16x32_bf16 v[18:21], v[172:175], v[196:199], v[18:21]
	v_mfma_f32_16x16x32_bf16 v[6:9], v[164:167], v[204:207], v[6:9]
	v_mfma_f32_16x16x32_bf16 v[2:5], v[172:175], v[204:207], v[2:5]
	v_mfma_f32_16x16x32_bf16 v[54:57], v[168:171], v[184:187], v[54:57]
	v_mfma_f32_16x16x32_bf16 v[50:53], v[176:179], v[184:187], v[50:53]
	v_mfma_f32_16x16x32_bf16 v[38:41], v[168:171], v[192:195], v[38:41]
	v_mfma_f32_16x16x32_bf16 v[34:37], v[176:179], v[192:195], v[34:37]
	v_mfma_f32_16x16x32_bf16 v[22:25], v[168:171], v[200:203], v[22:25]
	v_mfma_f32_16x16x32_bf16 v[18:21], v[176:179], v[200:203], v[18:21]
	v_mfma_f32_16x16x32_bf16 v[6:9], v[168:171], v[208:211], v[6:9]
	s_setprio 0
	v_mfma_f32_16x16x32_bf16 v[2:5], v[176:179], v[208:211], v[2:5]
	s_barrier
	s_add_i32 s78, 0, 0x18000
	s_add_i32 s79, 0, 0x1c000
	v_add_u32_e32 v160, s78, v251
	v_add_u32_e32 v176, s79, v251
	ds_read_b128 v[140:143], v160
	ds_read_b128 v[144:147], v160 offset:1024
	ds_read_b128 v[156:159], v160 offset:2048
	ds_read_b128 v[160:163], v160 offset:3072
	ds_read_b128 v[164:167], v176
	ds_read_b128 v[168:171], v176 offset:1024
	ds_read_b128 v[172:175], v176 offset:2048
	ds_read_b128 v[176:179], v176 offset:3072
	s_add_u32 s38, s72, 0xb0000
	s_addc_u32 s39, s73, 0
	s_mov_b32 m0, s52
	v_lshl_add_u64 v[216:217], s[38:39], 0, v[130:131]
	ds_read_b128 v[180:183], v253 offset:32768
	ds_read_b128 v[184:187], v253 offset:33792
	ds_read_b128 v[188:191], v253 offset:34816
	ds_read_b128 v[192:195], v253 offset:35840
	ds_read_b128 v[196:199], v253 offset:36864
	ds_read_b128 v[200:203], v253 offset:37888
	ds_read_b128 v[204:207], v253 offset:38912
	ds_read_b128 v[208:211], v253 offset:39936
	global_load_lds_dwordx4 v[216:217], off
	s_mov_b32 m0, s53
	v_lshl_add_u64 v[216:217], s[38:39], 0, v[132:133]
	global_load_lds_dwordx4 v[216:217], off
	s_waitcnt vmcnt(8) lgkmcnt(0)
	s_setprio 1
	s_barrier
	v_mfma_f32_16x16x32_bf16 v[126:129], v[140:143], v[180:183], v[126:129]
	v_mfma_f32_16x16x32_bf16 v[122:125], v[156:159], v[180:183], v[122:125]
	v_mfma_f32_16x16x32_bf16 v[110:113], v[140:143], v[188:191], v[110:113]
	v_mfma_f32_16x16x32_bf16 v[106:109], v[156:159], v[188:191], v[106:109]
	v_mfma_f32_16x16x32_bf16 v[94:97], v[140:143], v[196:199], v[94:97]
	v_mfma_f32_16x16x32_bf16 v[90:93], v[156:159], v[196:199], v[90:93]
	v_mfma_f32_16x16x32_bf16 v[78:81], v[140:143], v[204:207], v[78:81]
	v_mfma_f32_16x16x32_bf16 v[74:77], v[156:159], v[204:207], v[74:77]
	v_mfma_f32_16x16x32_bf16 v[126:129], v[144:147], v[184:187], v[126:129]
	v_mfma_f32_16x16x32_bf16 v[122:125], v[160:163], v[184:187], v[122:125]
	v_mfma_f32_16x16x32_bf16 v[110:113], v[144:147], v[192:195], v[110:113]
	v_mfma_f32_16x16x32_bf16 v[106:109], v[160:163], v[192:195], v[106:109]
	v_mfma_f32_16x16x32_bf16 v[94:97], v[144:147], v[200:203], v[94:97]
	v_mfma_f32_16x16x32_bf16 v[90:93], v[160:163], v[200:203], v[90:93]
	v_mfma_f32_16x16x32_bf16 v[78:81], v[144:147], v[208:211], v[78:81]
	v_mfma_f32_16x16x32_bf16 v[74:77], v[160:163], v[208:211], v[74:77]
	v_mfma_f32_16x16x32_bf16 v[118:121], v[164:167], v[180:183], v[118:121]
	v_mfma_f32_16x16x32_bf16 v[114:117], v[172:175], v[180:183], v[114:117]
	v_mfma_f32_16x16x32_bf16 v[102:105], v[164:167], v[188:191], v[102:105]
	v_mfma_f32_16x16x32_bf16 v[98:101], v[172:175], v[188:191], v[98:101]
	v_mfma_f32_16x16x32_bf16 v[86:89], v[164:167], v[196:199], v[86:89]
	v_mfma_f32_16x16x32_bf16 v[82:85], v[172:175], v[196:199], v[82:85]
	v_mfma_f32_16x16x32_bf16 v[70:73], v[164:167], v[204:207], v[70:73]
	v_mfma_f32_16x16x32_bf16 v[66:69], v[172:175], v[204:207], v[66:69]
	v_mfma_f32_16x16x32_bf16 v[118:121], v[168:171], v[184:187], v[118:121]
	v_mfma_f32_16x16x32_bf16 v[114:117], v[176:179], v[184:187], v[114:117]
	v_mfma_f32_16x16x32_bf16 v[102:105], v[168:171], v[192:195], v[102:105]
	v_mfma_f32_16x16x32_bf16 v[98:101], v[176:179], v[192:195], v[98:101]
	v_mfma_f32_16x16x32_bf16 v[86:89], v[168:171], v[200:203], v[86:89]
	v_mfma_f32_16x16x32_bf16 v[82:85], v[176:179], v[200:203], v[82:85]
	v_mfma_f32_16x16x32_bf16 v[70:73], v[168:171], v[208:211], v[70:73]
	s_setprio 0
	v_mfma_f32_16x16x32_bf16 v[66:69], v[176:179], v[208:211], v[66:69]
	s_barrier
	s_add_i32 s38, s78, s49
	v_lshl_add_u64 v[148:149], v[148:149], 0, s[70:71]
	s_mov_b32 m0, s38
	ds_read_b128 v[180:183], v253 offset:49152
	ds_read_b128 v[184:187], v253 offset:50176
	ds_read_b128 v[188:191], v253 offset:51200
	ds_read_b128 v[192:195], v253 offset:52224
	ds_read_b128 v[196:199], v253 offset:53248
	ds_read_b128 v[200:203], v253 offset:54272
	ds_read_b128 v[204:207], v253 offset:55296
	ds_read_b128 v[208:211], v253 offset:56320
	global_load_lds_dwordx4 v[148:149], off
	s_add_i32 m0, s38, 0x2000
	s_add_u32 s26, s26, 0xb0080
	v_lshl_add_u64 v[148:149], v[150:151], 0, s[70:71]
	s_addc_u32 s27, s27, 0
	s_add_i32 s38, s79, s49
	global_load_lds_dwordx4 v[148:149], off
	s_mov_b32 m0, s38
	v_lshl_add_u64 v[148:149], s[26:27], 0, v[0:1]
	global_load_lds_dwordx4 v[148:149], off
	s_add_i32 m0, s38, 0x2000
	v_lshl_add_u64 v[148:149], s[26:27], 0, v[134:135]
	global_load_lds_dwordx4 v[148:149], off
	s_mov_b32 m0, s74
	v_lshl_add_u64 v[148:149], v[212:213], 0, s[70:71]
	global_load_lds_dwordx4 v[148:149], off
	s_mov_b32 m0, s75
	v_lshl_add_u64 v[148:149], v[214:215], 0, s[70:71]
	global_load_lds_dwordx4 v[148:149], off
	s_waitcnt vmcnt(8) lgkmcnt(0)
	s_setprio 1
	s_barrier
	v_mfma_f32_16x16x32_bf16 v[62:65], v[140:143], v[180:183], v[62:65]
	v_mfma_f32_16x16x32_bf16 v[58:61], v[156:159], v[180:183], v[58:61]
	v_mfma_f32_16x16x32_bf16 v[46:49], v[140:143], v[188:191], v[46:49]
	v_mfma_f32_16x16x32_bf16 v[42:45], v[156:159], v[188:191], v[42:45]
	v_mfma_f32_16x16x32_bf16 v[30:33], v[140:143], v[196:199], v[30:33]
	v_mfma_f32_16x16x32_bf16 v[26:29], v[156:159], v[196:199], v[26:29]
	v_mfma_f32_16x16x32_bf16 v[14:17], v[140:143], v[204:207], v[14:17]
	v_mfma_f32_16x16x32_bf16 v[10:13], v[156:159], v[204:207], v[10:13]
	v_mfma_f32_16x16x32_bf16 v[62:65], v[144:147], v[184:187], v[62:65]
	v_mfma_f32_16x16x32_bf16 v[58:61], v[160:163], v[184:187], v[58:61]
	v_mfma_f32_16x16x32_bf16 v[46:49], v[144:147], v[192:195], v[46:49]
	v_mfma_f32_16x16x32_bf16 v[42:45], v[160:163], v[192:195], v[42:45]
	v_mfma_f32_16x16x32_bf16 v[30:33], v[144:147], v[200:203], v[30:33]
	v_mfma_f32_16x16x32_bf16 v[26:29], v[160:163], v[200:203], v[26:29]
	v_mfma_f32_16x16x32_bf16 v[14:17], v[144:147], v[208:211], v[14:17]
	v_mfma_f32_16x16x32_bf16 v[10:13], v[160:163], v[208:211], v[10:13]
	v_mfma_f32_16x16x32_bf16 v[54:57], v[164:167], v[180:183], v[54:57]
	v_mfma_f32_16x16x32_bf16 v[50:53], v[172:175], v[180:183], v[50:53]
	v_mfma_f32_16x16x32_bf16 v[38:41], v[164:167], v[188:191], v[38:41]
	v_mfma_f32_16x16x32_bf16 v[34:37], v[172:175], v[188:191], v[34:37]
	v_mfma_f32_16x16x32_bf16 v[22:25], v[164:167], v[196:199], v[22:25]
	v_mfma_f32_16x16x32_bf16 v[18:21], v[172:175], v[196:199], v[18:21]
	v_mfma_f32_16x16x32_bf16 v[6:9], v[164:167], v[204:207], v[6:9]
	v_mfma_f32_16x16x32_bf16 v[2:5], v[172:175], v[204:207], v[2:5]
	v_mfma_f32_16x16x32_bf16 v[54:57], v[168:171], v[184:187], v[54:57]
	v_mfma_f32_16x16x32_bf16 v[50:53], v[176:179], v[184:187], v[50:53]
	v_mfma_f32_16x16x32_bf16 v[38:41], v[168:171], v[192:195], v[38:41]
	v_mfma_f32_16x16x32_bf16 v[34:37], v[176:179], v[192:195], v[34:37]
	v_mfma_f32_16x16x32_bf16 v[22:25], v[168:171], v[200:203], v[22:25]
	v_mfma_f32_16x16x32_bf16 v[18:21], v[176:179], v[200:203], v[18:21]
	v_mfma_f32_16x16x32_bf16 v[6:9], v[168:171], v[208:211], v[6:9]
	s_setprio 0
	v_mfma_f32_16x16x32_bf16 v[2:5], v[176:179], v[208:211], v[2:5]
	s_barrier
	s_add_u32 vcc_lo, vcc_lo, 0x100
	s_addc_u32 vcc_hi, vcc_hi, 0
	s_cmp_ge_u32 s9, s28
	s_mov_b64 s[38:39], s[60:61]
	s_mov_b32 s26, s9
	s_cbranch_scc0 .LBB0_1000
	s_and_b64 vcc, exec, s[22:23]
	s_cbranch_vccz .LBB0_1003

.LBB0_1054:
	s_add_i32 s96, s26, 2
	s_add_u32 s36, s24, 0x100
	s_addc_u32 s37, s25, 0
	s_add_i32 s9, 0, 0x10000
	s_cmp_eq_u32 s93, s26
	s_cselect_b32 s39, s15, s37
	s_cselect_b32 s38, s14, s36
	v_add_u32_e32 v148, s9, v177
	s_cselect_b32 s27, s23, s95
	s_cselect_b32 s26, s22, s94
	s_add_i32 s78, 0, 0x14000
	ds_read_b128 v[140:143], v148
	ds_read_b128 v[144:147], v148 offset:1024
	ds_read_b128 v[156:159], v148 offset:2048
	ds_read_b128 v[160:163], v148 offset:3072
	v_add_u32_e32 v148, s78, v177
	ds_read_b128 v[164:167], v148
	ds_read_b128 v[168:171], v148 offset:1024
	ds_read_b128 v[172:175], v148 offset:2048
	ds_read_b128 v[180:183], v148 offset:3072
	v_lshl_add_u64 v[148:149], s[24:25], 0, v[136:137]
	s_add_i32 m0, s29, 0xc000
	ds_read_b128 v[184:187], v179
	ds_read_b128 v[188:191], v179 offset:1024
	ds_read_b128 v[192:195], v179 offset:2048
	ds_read_b128 v[196:199], v179 offset:3072
	ds_read_b128 v[200:203], v179 offset:4096
	ds_read_b128 v[204:207], v179 offset:5120
	ds_read_b128 v[208:211], v179 offset:6144
	ds_read_b128 v[212:215], v179 offset:7168
	global_load_lds_dwordx4 v[148:149], off
	s_add_i32 m0, s29, 0xe000
	v_lshl_add_u64 v[148:149], s[24:25], 0, v[138:139]
	global_load_lds_dwordx4 v[148:149], off
	s_waitcnt vmcnt(8) lgkmcnt(0)
	s_setprio 1
	s_barrier
	v_mfma_f32_16x16x32_bf16 v[126:129], v[140:143], v[184:187], v[126:129]
	v_mfma_f32_16x16x32_bf16 v[122:125], v[156:159], v[184:187], v[122:125]
	v_mfma_f32_16x16x32_bf16 v[110:113], v[140:143], v[192:195], v[110:113]
	v_mfma_f32_16x16x32_bf16 v[106:109], v[156:159], v[192:195], v[106:109]
	v_mfma_f32_16x16x32_bf16 v[94:97], v[140:143], v[200:203], v[94:97]
	v_mfma_f32_16x16x32_bf16 v[90:93], v[156:159], v[200:203], v[90:93]
	v_mfma_f32_16x16x32_bf16 v[78:81], v[140:143], v[208:211], v[78:81]
	v_mfma_f32_16x16x32_bf16 v[74:77], v[156:159], v[208:211], v[74:77]
	v_mfma_f32_16x16x32_bf16 v[126:129], v[144:147], v[188:191], v[126:129]
	v_mfma_f32_16x16x32_bf16 v[122:125], v[160:163], v[188:191], v[122:125]
	v_mfma_f32_16x16x32_bf16 v[110:113], v[144:147], v[196:199], v[110:113]
	v_mfma_f32_16x16x32_bf16 v[106:109], v[160:163], v[196:199], v[106:109]
	v_mfma_f32_16x16x32_bf16 v[94:97], v[144:147], v[204:207], v[94:97]
	v_mfma_f32_16x16x32_bf16 v[90:93], v[160:163], v[204:207], v[90:93]
	v_mfma_f32_16x16x32_bf16 v[78:81], v[144:147], v[212:215], v[78:81]
	v_mfma_f32_16x16x32_bf16 v[74:77], v[160:163], v[212:215], v[74:77]
	v_mfma_f32_16x16x32_bf16 v[118:121], v[164:167], v[184:187], v[118:121]
	v_mfma_f32_16x16x32_bf16 v[114:117], v[172:175], v[184:187], v[114:117]
	v_mfma_f32_16x16x32_bf16 v[102:105], v[164:167], v[192:195], v[102:105]
	v_mfma_f32_16x16x32_bf16 v[98:101], v[172:175], v[192:195], v[98:101]
	v_mfma_f32_16x16x32_bf16 v[86:89], v[164:167], v[200:203], v[86:89]
	v_mfma_f32_16x16x32_bf16 v[82:85], v[172:175], v[200:203], v[82:85]
	v_mfma_f32_16x16x32_bf16 v[70:73], v[164:167], v[208:211], v[70:73]
	v_mfma_f32_16x16x32_bf16 v[66:69], v[172:175], v[208:211], v[66:69]
	v_mfma_f32_16x16x32_bf16 v[118:121], v[168:171], v[188:191], v[118:121]
	v_mfma_f32_16x16x32_bf16 v[114:117], v[180:183], v[188:191], v[114:117]
	v_mfma_f32_16x16x32_bf16 v[102:105], v[168:171], v[196:199], v[102:105]
	v_mfma_f32_16x16x32_bf16 v[98:101], v[180:183], v[196:199], v[98:101]
	v_mfma_f32_16x16x32_bf16 v[86:89], v[168:171], v[204:207], v[86:89]
	v_mfma_f32_16x16x32_bf16 v[82:85], v[180:183], v[204:207], v[82:85]
	v_mfma_f32_16x16x32_bf16 v[70:73], v[168:171], v[212:215], v[70:73]
	s_setprio 0
	v_mfma_f32_16x16x32_bf16 v[66:69], v[180:183], v[212:215], v[66:69]
	s_barrier
	s_add_i32 s9, s9, s28
	v_lshl_add_u64 v[148:149], s[26:27], 0, v[0:1]
	s_mov_b32 m0, s9
	ds_read_b128 v[184:187], v179 offset:16384
	ds_read_b128 v[188:191], v179 offset:17408
	ds_read_b128 v[192:195], v179 offset:18432
	ds_read_b128 v[196:199], v179 offset:19456
	ds_read_b128 v[200:203], v179 offset:20480
	ds_read_b128 v[204:207], v179 offset:21504
	ds_read_b128 v[208:211], v179 offset:22528
	ds_read_b128 v[212:215], v179 offset:23552
	global_load_lds_dwordx4 v[148:149], off
	s_add_i32 m0, s9, 0x2000
	s_add_u32 s24, s26, 0xb0000
	v_lshl_add_u64 v[150:151], s[26:27], 0, v[134:135]
	s_addc_u32 s25, s27, 0
	s_add_i32 s9, s78, s28
	global_load_lds_dwordx4 v[150:151], off
	v_lshl_add_u64 v[216:217], s[24:25], 0, v[0:1]
	s_mov_b32 m0, s9
	v_lshl_add_u64 v[218:219], s[38:39], 0, v[132:133]
	global_load_lds_dwordx4 v[216:217], off
	s_add_i32 m0, s9, 0x2000
	v_lshl_add_u64 v[216:217], s[24:25], 0, v[134:135]
	global_load_lds_dwordx4 v[216:217], off
	s_mov_b32 m0, s29
	v_lshl_add_u64 v[216:217], s[38:39], 0, v[130:131]
	global_load_lds_dwordx4 v[216:217], off
	s_mov_b32 m0, s49
	s_nop 0
	global_load_lds_dwordx4 v[218:219], off
	s_waitcnt vmcnt(8) lgkmcnt(0)
	s_setprio 1
	s_barrier
	v_mfma_f32_16x16x32_bf16 v[62:65], v[140:143], v[184:187], v[62:65]
	v_mfma_f32_16x16x32_bf16 v[58:61], v[156:159], v[184:187], v[58:61]
	v_mfma_f32_16x16x32_bf16 v[46:49], v[140:143], v[192:195], v[46:49]
	v_mfma_f32_16x16x32_bf16 v[42:45], v[156:159], v[192:195], v[42:45]
	v_mfma_f32_16x16x32_bf16 v[30:33], v[140:143], v[200:203], v[30:33]
	v_mfma_f32_16x16x32_bf16 v[26:29], v[156:159], v[200:203], v[26:29]
	v_mfma_f32_16x16x32_bf16 v[14:17], v[140:143], v[208:211], v[14:17]
	v_mfma_f32_16x16x32_bf16 v[10:13], v[156:159], v[208:211], v[10:13]
	v_mfma_f32_16x16x32_bf16 v[62:65], v[144:147], v[188:191], v[62:65]
	v_mfma_f32_16x16x32_bf16 v[58:61], v[160:163], v[188:191], v[58:61]
	v_mfma_f32_16x16x32_bf16 v[46:49], v[144:147], v[196:199], v[46:49]
	v_mfma_f32_16x16x32_bf16 v[42:45], v[160:163], v[196:199], v[42:45]
	v_mfma_f32_16x16x32_bf16 v[30:33], v[144:147], v[204:207], v[30:33]
	v_mfma_f32_16x16x32_bf16 v[26:29], v[160:163], v[204:207], v[26:29]
	v_mfma_f32_16x16x32_bf16 v[14:17], v[144:147], v[212:215], v[14:17]
	v_mfma_f32_16x16x32_bf16 v[10:13], v[160:163], v[212:215], v[10:13]
	v_mfma_f32_16x16x32_bf16 v[54:57], v[164:167], v[184:187], v[54:57]
	v_mfma_f32_16x16x32_bf16 v[50:53], v[172:175], v[184:187], v[50:53]
	v_mfma_f32_16x16x32_bf16 v[38:41], v[164:167], v[192:195], v[38:41]
	v_mfma_f32_16x16x32_bf16 v[34:37], v[172:175], v[192:195], v[34:37]
	v_mfma_f32_16x16x32_bf16 v[22:25], v[164:167], v[200:203], v[22:25]
	v_mfma_f32_16x16x32_bf16 v[18:21], v[172:175], v[200:203], v[18:21]
	v_mfma_f32_16x16x32_bf16 v[6:9], v[164:167], v[208:211], v[6:9]
	v_mfma_f32_16x16x32_bf16 v[2:5], v[172:175], v[208:211], v[2:5]
	v_mfma_f32_16x16x32_bf16 v[54:57], v[168:171], v[188:191], v[54:57]
	v_mfma_f32_16x16x32_bf16 v[50:53], v[180:183], v[188:191], v[50:53]
	v_mfma_f32_16x16x32_bf16 v[38:41], v[168:171], v[196:199], v[38:41]
	v_mfma_f32_16x16x32_bf16 v[34:37], v[180:183], v[196:199], v[34:37]
	v_mfma_f32_16x16x32_bf16 v[22:25], v[168:171], v[204:207], v[22:25]
	v_mfma_f32_16x16x32_bf16 v[18:21], v[180:183], v[204:207], v[18:21]
	v_mfma_f32_16x16x32_bf16 v[6:9], v[168:171], v[212:215], v[6:9]
	s_setprio 0
	v_mfma_f32_16x16x32_bf16 v[2:5], v[180:183], v[212:215], v[2:5]
	s_barrier
	s_add_i32 s9, 0, 0x18000
	s_add_i32 s78, 0, 0x1c000
	v_add_u32_e32 v160, s9, v177
	v_add_u32_e32 v180, s78, v177
	ds_read_b128 v[140:143], v160
	ds_read_b128 v[144:147], v160 offset:1024
	ds_read_b128 v[156:159], v160 offset:2048
	ds_read_b128 v[160:163], v160 offset:3072
	ds_read_b128 v[164:167], v180
	ds_read_b128 v[168:171], v180 offset:1024
	ds_read_b128 v[172:175], v180 offset:2048
	ds_read_b128 v[180:183], v180 offset:3072
	s_add_u32 s24, s38, 0xb0000
	s_addc_u32 s25, s39, 0
	s_mov_b32 m0, s50
	v_lshl_add_u64 v[220:221], s[24:25], 0, v[130:131]
	ds_read_b128 v[184:187], v179 offset:32768
	ds_read_b128 v[188:191], v179 offset:33792
	ds_read_b128 v[192:195], v179 offset:34816
	ds_read_b128 v[196:199], v179 offset:35840
	ds_read_b128 v[200:203], v179 offset:36864
	ds_read_b128 v[204:207], v179 offset:37888
	ds_read_b128 v[208:211], v179 offset:38912
	ds_read_b128 v[212:215], v179 offset:39936
	global_load_lds_dwordx4 v[220:221], off
	s_mov_b32 m0, s51
	v_lshl_add_u64 v[220:221], s[24:25], 0, v[132:133]
	global_load_lds_dwordx4 v[220:221], off
	s_waitcnt vmcnt(8) lgkmcnt(0)
	s_setprio 1
	s_barrier
	v_mfma_f32_16x16x32_bf16 v[126:129], v[140:143], v[184:187], v[126:129]
	v_mfma_f32_16x16x32_bf16 v[122:125], v[156:159], v[184:187], v[122:125]
	v_mfma_f32_16x16x32_bf16 v[110:113], v[140:143], v[192:195], v[110:113]
	v_mfma_f32_16x16x32_bf16 v[106:109], v[156:159], v[192:195], v[106:109]
	v_mfma_f32_16x16x32_bf16 v[94:97], v[140:143], v[200:203], v[94:97]
	v_mfma_f32_16x16x32_bf16 v[90:93], v[156:159], v[200:203], v[90:93]
	v_mfma_f32_16x16x32_bf16 v[78:81], v[140:143], v[208:211], v[78:81]
	v_mfma_f32_16x16x32_bf16 v[74:77], v[156:159], v[208:211], v[74:77]
	v_mfma_f32_16x16x32_bf16 v[126:129], v[144:147], v[188:191], v[126:129]
	v_mfma_f32_16x16x32_bf16 v[122:125], v[160:163], v[188:191], v[122:125]
	v_mfma_f32_16x16x32_bf16 v[110:113], v[144:147], v[196:199], v[110:113]
	v_mfma_f32_16x16x32_bf16 v[106:109], v[160:163], v[196:199], v[106:109]
	v_mfma_f32_16x16x32_bf16 v[94:97], v[144:147], v[204:207], v[94:97]
	v_mfma_f32_16x16x32_bf16 v[90:93], v[160:163], v[204:207], v[90:93]
	v_mfma_f32_16x16x32_bf16 v[78:81], v[144:147], v[212:215], v[78:81]
	v_mfma_f32_16x16x32_bf16 v[74:77], v[160:163], v[212:215], v[74:77]
	v_mfma_f32_16x16x32_bf16 v[118:121], v[164:167], v[184:187], v[118:121]
	v_mfma_f32_16x16x32_bf16 v[114:117], v[172:175], v[184:187], v[114:117]
	v_mfma_f32_16x16x32_bf16 v[102:105], v[164:167], v[192:195], v[102:105]
	v_mfma_f32_16x16x32_bf16 v[98:101], v[172:175], v[192:195], v[98:101]
	v_mfma_f32_16x16x32_bf16 v[86:89], v[164:167], v[200:203], v[86:89]
	v_mfma_f32_16x16x32_bf16 v[82:85], v[172:175], v[200:203], v[82:85]
	v_mfma_f32_16x16x32_bf16 v[70:73], v[164:167], v[208:211], v[70:73]
	v_mfma_f32_16x16x32_bf16 v[66:69], v[172:175], v[208:211], v[66:69]
	v_mfma_f32_16x16x32_bf16 v[118:121], v[168:171], v[188:191], v[118:121]
	v_mfma_f32_16x16x32_bf16 v[114:117], v[180:183], v[188:191], v[114:117]
	v_mfma_f32_16x16x32_bf16 v[102:105], v[168:171], v[196:199], v[102:105]
	v_mfma_f32_16x16x32_bf16 v[98:101], v[180:183], v[196:199], v[98:101]
	v_mfma_f32_16x16x32_bf16 v[86:89], v[168:171], v[204:207], v[86:89]
	v_mfma_f32_16x16x32_bf16 v[82:85], v[180:183], v[204:207], v[82:85]
	v_mfma_f32_16x16x32_bf16 v[70:73], v[168:171], v[212:215], v[70:73]
	s_setprio 0
	v_mfma_f32_16x16x32_bf16 v[66:69], v[180:183], v[212:215], v[66:69]
	s_barrier
	s_add_i32 s9, s9, s28
	v_lshl_add_u64 v[148:149], v[148:149], 0, s[70:71]
	s_mov_b32 m0, s9
	ds_read_b128 v[184:187], v179 offset:49152
	ds_read_b128 v[188:191], v179 offset:50176
	ds_read_b128 v[192:195], v179 offset:51200
	ds_read_b128 v[196:199], v179 offset:52224
	ds_read_b128 v[200:203], v179 offset:53248
	ds_read_b128 v[204:207], v179 offset:54272
	ds_read_b128 v[208:211], v179 offset:55296
	ds_read_b128 v[212:215], v179 offset:56320
	global_load_lds_dwordx4 v[148:149], off
	s_add_i32 m0, s9, 0x2000
	s_add_u32 s24, s26, 0xb0080
	v_lshl_add_u64 v[148:149], v[150:151], 0, s[70:71]
	s_addc_u32 s25, s27, 0
	s_add_i32 s9, s78, s28
	global_load_lds_dwordx4 v[148:149], off
	s_mov_b32 m0, s9
	v_lshl_add_u64 v[148:149], s[24:25], 0, v[0:1]
	global_load_lds_dwordx4 v[148:149], off
	s_add_i32 m0, s9, 0x2000
	v_lshl_add_u64 v[148:149], s[24:25], 0, v[134:135]
	global_load_lds_dwordx4 v[148:149], off
	s_mov_b32 m0, s52
	v_lshl_add_u64 v[148:149], v[216:217], 0, s[70:71]
	global_load_lds_dwordx4 v[148:149], off
	s_mov_b32 m0, s53
	v_lshl_add_u64 v[148:149], v[218:219], 0, s[70:71]
	global_load_lds_dwordx4 v[148:149], off
	s_waitcnt vmcnt(8) lgkmcnt(0)
	s_setprio 1
	s_barrier
	v_mfma_f32_16x16x32_bf16 v[62:65], v[140:143], v[184:187], v[62:65]
	v_mfma_f32_16x16x32_bf16 v[58:61], v[156:159], v[184:187], v[58:61]
	v_mfma_f32_16x16x32_bf16 v[46:49], v[140:143], v[192:195], v[46:49]
	v_mfma_f32_16x16x32_bf16 v[42:45], v[156:159], v[192:195], v[42:45]
	v_mfma_f32_16x16x32_bf16 v[30:33], v[140:143], v[200:203], v[30:33]
	v_mfma_f32_16x16x32_bf16 v[26:29], v[156:159], v[200:203], v[26:29]
	v_mfma_f32_16x16x32_bf16 v[14:17], v[140:143], v[208:211], v[14:17]
	v_mfma_f32_16x16x32_bf16 v[10:13], v[156:159], v[208:211], v[10:13]
	v_mfma_f32_16x16x32_bf16 v[62:65], v[144:147], v[188:191], v[62:65]
	v_mfma_f32_16x16x32_bf16 v[58:61], v[160:163], v[188:191], v[58:61]
	v_mfma_f32_16x16x32_bf16 v[46:49], v[144:147], v[196:199], v[46:49]
	v_mfma_f32_16x16x32_bf16 v[42:45], v[160:163], v[196:199], v[42:45]
	v_mfma_f32_16x16x32_bf16 v[30:33], v[144:147], v[204:207], v[30:33]
	v_mfma_f32_16x16x32_bf16 v[26:29], v[160:163], v[204:207], v[26:29]
	v_mfma_f32_16x16x32_bf16 v[14:17], v[144:147], v[212:215], v[14:17]
	v_mfma_f32_16x16x32_bf16 v[10:13], v[160:163], v[212:215], v[10:13]
	v_mfma_f32_16x16x32_bf16 v[54:57], v[164:167], v[184:187], v[54:57]
	v_mfma_f32_16x16x32_bf16 v[50:53], v[172:175], v[184:187], v[50:53]
	v_mfma_f32_16x16x32_bf16 v[38:41], v[164:167], v[192:195], v[38:41]
	v_mfma_f32_16x16x32_bf16 v[34:37], v[172:175], v[192:195], v[34:37]
	v_mfma_f32_16x16x32_bf16 v[22:25], v[164:167], v[200:203], v[22:25]
	v_mfma_f32_16x16x32_bf16 v[18:21], v[172:175], v[200:203], v[18:21]
	v_mfma_f32_16x16x32_bf16 v[6:9], v[164:167], v[208:211], v[6:9]
	v_mfma_f32_16x16x32_bf16 v[2:5], v[172:175], v[208:211], v[2:5]
	v_mfma_f32_16x16x32_bf16 v[54:57], v[168:171], v[188:191], v[54:57]
	v_mfma_f32_16x16x32_bf16 v[50:53], v[180:183], v[188:191], v[50:53]
	v_mfma_f32_16x16x32_bf16 v[38:41], v[168:171], v[196:199], v[38:41]
	v_mfma_f32_16x16x32_bf16 v[34:37], v[180:183], v[196:199], v[34:37]
	v_mfma_f32_16x16x32_bf16 v[22:25], v[168:171], v[204:207], v[22:25]
	v_mfma_f32_16x16x32_bf16 v[18:21], v[180:183], v[204:207], v[18:21]
	v_mfma_f32_16x16x32_bf16 v[6:9], v[168:171], v[212:215], v[6:9]
	s_setprio 0
	v_mfma_f32_16x16x32_bf16 v[2:5], v[180:183], v[212:215], v[2:5]
	s_barrier
	s_add_u32 s94, s94, 0x100
	s_addc_u32 s95, s95, 0
	s_cmp_ge_u32 s96, s92
	s_mov_b64 s[24:25], s[36:37]
	s_mov_b32 s26, s96
	s_cbranch_scc0 .LBB0_1054
	s_and_b64 vcc, exec, s[12:13]
	s_cbranch_vccz .LBB0_1057
